# hand-written out-proj epilogue: residual add in place, all loads of a stage issued together, shared exchange block, no waits behind write-through stores
# speedup vs baseline: 1.0331x; 1.0115x over previous
.LBB0_988:
	s_waitcnt vmcnt(0)
	v_readlane_b32 s52, v255, 2
	v_readlane_b32 s60, v255, 22
	s_cmp_lg_u32 s39, 4
	v_readlane_b32 s63, v254, 32
	v_readlane_b32 s75, v254, 33
	s_movk_i32 s64, 0x2000
	s_movk_i32 s68, 0x1fff
	s_mov_b32 s72, 0x800000
	s_movk_i32 s77, 0x1ff
	s_movk_i32 s48, 0x7ff
	s_movk_i32 s49, 0xeff
	s_mov_b32 s50, 0x1ffff
	s_mov_b32 s51, 0x23fff
	s_mov_b32 s54, 0x100000
	s_mov_b64 s[56:57], 0x300000
	v_readlane_b32 s44, v255, 4
	v_readlane_b32 s45, v255, 5
	v_readlane_b32 s58, v255, 7
	v_readlane_b32 s53, v255, 3
	v_readlane_b32 s33, v255, 16
	v_readlane_b32 s61, v255, 23
	v_mov_b32_e32 v240, v251
	s_barrier
	v_readlane_b32 s59, v255, 8
	s_cbranch_scc1 .LBB0_1145
	s_load_dwordx2 s[2:3], s[0:1], 0xd0
	s_load_dwordx2 s[4:5], s[0:1], 0xc8
	v_readlane_b32 s34, v254, 36
	v_readlane_b32 s35, v255, 29
	v_readlane_b32 s36, v255, 20
	v_mbcnt_lo_u32_b32 v236, -1, 0
	v_mbcnt_hi_u32_b32 v236, -1, v236
	v_and_b32_e32 v237, 15, v236
	v_lshrrev_b32_e32 v238, 4, v236
	v_lshlrev_b32_e32 v210, 5, v238
	v_lshl_add_u32 v211, v237, 12, v210
	v_lshlrev_b32_e32 v212, 4, v238
	v_lshl_add_u32 v213, v237, 11, v212
	v_lshl_add_u32 v212, v237, 12, v212
	v_and_b32_e32 v239, 31, v236
	v_lshl_add_u32 v239, s33, 5, v239
	v_lshlrev_b32_e32 v215, 4, v239
	v_lshlrev_b32_e32 v216, 2, v239
	s_lshl_b32 s37, s36, 10
	s_lshr_b32 s39, s35, 3
	s_add_u32 s37, s37, s39
	v_lshl_add_u32 v214, v237, 4, s37
	s_lshl_b32 s37, s36, 8
	v_lshl_add_u32 v217, v237, 2, s37
	s_sub_u32 s37, s34, 32
	s_lshr_b32 s37, s37, 2
	s_add_u32 s37, s37, 1
	s_cmp_lt_u32 s34, 32
	s_cselect_b32 s37, 0, s37
	s_lshl_b32 s39, s34, 8
	s_lshl_b32 s40, s36, 6
	s_add_u32 s39, s39, s40
	s_lshl_b32 s40, s74, 10
	s_lshl_b32 s41, s35, 2
	s_add_u32 s40, s40, s41
	s_mul_i32 s41, s60, 5
	s_add_u32 s41, s41, s37
	s_mul_i32 s41, s41, 0x3000
	s_add_u32 s41, s41, s40
	s_add_u32 s41, s41, 0x100000
	s_waitcnt lgkmcnt(0)
	s_add_u32 s10, s2, s41
	s_addc_u32 s11, s3, 0
	s_add_u32 s12, s10, 0xf000
	s_addc_u32 s13, s11, 0
	s_add_u32 s10, s10, 0x2000
	s_addc_u32 s11, s11, 0
	s_mul_i32 s41, s60, 48
	s_add_u32 s41, s41, s34
	s_lshl_b32 s41, s41, 8
	s_add_u32 s24, s2, s41
	s_addc_u32 s25, s3, 0
	s_add_u32 s26, s24, 0x40000
	s_addc_u32 s27, s25, 0
	s_add_u32 s24, s24, 0x10000
	s_addc_u32 s25, s25, 0
	s_mul_i32 s41, s60, 0x30000
	s_lshl_b32 s28, s34, 12
	s_add_u32 s41, s41, s28
	s_add_u32 s41, s41, 0xe500000
	s_add_u32 s22, s2, s41
	s_addc_u32 s23, s3, 0
	s_cmp_eq_u32 s60, 3
	s_cbranch_scc1 .Lo4_gfinal
	s_load_dwordx2 s[20:21], s[0:1], 0x50
	s_add_u32 s41, s60, 1
	s_lshl_b32 s41, s41, 12
	s_add_u32 s41, s41, s40
	s_branch .Lo4_gdone
.Lo4_gfinal:
	s_load_dwordx2 s[20:21], s[0:1], 0xc0
	s_mov_b32 s41, s40
.Lo4_gdone:
	s_waitcnt lgkmcnt(0)
	s_add_u32 s20, s20, s41
	s_addc_u32 s21, s21, 0
	s_cmp_eq_u32 s60, 3
	s_cbranch_scc1 .Lo4_ofinal
	s_lshl_b32 s41, s39, 11
	s_lshl_b32 s28, s74, 9
	s_add_u32 s41, s41, s28
	s_lshl_b32 s28, s35, 1
	s_add_u32 s41, s41, s28
	s_add_u32 s41, s41, 0xe600000
	s_add_u32 s8, s2, s41
	s_addc_u32 s9, s3, 0
	s_branch .Lo4_odone
.Lo4_ofinal:
	s_lshl_b32 s41, s39, 12
	s_add_u32 s41, s41, s40
	s_add_u32 s8, s4, s41
	s_addc_u32 s9, s5, 0
.Lo4_odone:
	s_cmp_eq_u32 s60, 0
	s_cbranch_scc1 .Lo4_first
	s_lshl_b32 s41, s39, 12
	s_lshl_b32 s28, s74, 10
	s_add_u32 s41, s41, s28
	s_lshl_b32 s28, s35, 1
	s_add_u32 s41, s41, s28
	s_add_u32 s6, s4, s41
	s_addc_u32 s7, s5, 0
	global_load_dwordx4 v[130:133], v210, s[10:11] offset:0
	global_load_dwordx4 v[134:137], v210, s[10:11] offset:16
	global_load_dwordx4 v[138:141], v210, s[10:11] offset:512
	global_load_dwordx4 v[142:145], v210, s[10:11] offset:528
	global_load_dwordx4 v[146:149], v212, s[6:7]
	global_load_dwordx4 v[150:153], v212, s[6:7] offset:256
	s_add_u32 s6, s6, 0x10000
	s_addc_u32 s7, s7, 0
	global_load_dwordx4 v[154:157], v212, s[6:7]
	global_load_dwordx4 v[158:161], v212, s[6:7] offset:256
	s_add_u32 s6, s6, 0x10000
	s_addc_u32 s7, s7, 0
	global_load_dwordx4 v[162:165], v212, s[6:7]
	global_load_dwordx4 v[166:169], v212, s[6:7] offset:256
	s_add_u32 s6, s6, 0x10000
	s_addc_u32 s7, s7, 0
	global_load_dwordx4 v[170:173], v212, s[6:7]
	global_load_dwordx4 v[174:177], v212, s[6:7] offset:256
	s_add_u32 s6, s6, 0x50000
	s_addc_u32 s7, s7, 0
	global_load_dwordx4 v[178:181], v212, s[6:7]
	global_load_dwordx4 v[182:185], v212, s[6:7] offset:256
	s_add_u32 s6, s6, 0x10000
	s_addc_u32 s7, s7, 0
	global_load_dwordx4 v[186:189], v212, s[6:7]
	global_load_dwordx4 v[190:193], v212, s[6:7] offset:256
	s_add_u32 s6, s6, 0x10000
	s_addc_u32 s7, s7, 0
	global_load_dwordx4 v[194:197], v212, s[6:7]
	global_load_dwordx4 v[198:201], v212, s[6:7] offset:256
	s_add_u32 s6, s6, 0x10000
	s_addc_u32 s7, s7, 0
	global_load_dwordx4 v[202:205], v212, s[6:7]
	global_load_dwordx4 v[206:209], v212, s[6:7] offset:256
	s_waitcnt vmcnt(8)
	v_lshlrev_b32_e32 v236, 16, v146
	v_and_b32_e32 v237, 0xffff0000, v146
	v_pk_fma_f32 v[126:127], v[126:127], v[130:131], v[236:237]
	v_lshlrev_b32_e32 v236, 16, v147
	v_and_b32_e32 v237, 0xffff0000, v147
	v_pk_fma_f32 v[128:129], v[128:129], v[132:133], v[236:237]
	v_lshlrev_b32_e32 v236, 16, v148
	v_and_b32_e32 v237, 0xffff0000, v148
	v_pk_fma_f32 v[122:123], v[122:123], v[134:135], v[236:237]
	v_lshlrev_b32_e32 v236, 16, v149
	v_and_b32_e32 v237, 0xffff0000, v149
	v_pk_fma_f32 v[124:125], v[124:125], v[136:137], v[236:237]
	v_lshlrev_b32_e32 v236, 16, v150
	v_and_b32_e32 v237, 0xffff0000, v150
	v_pk_fma_f32 v[118:119], v[118:119], v[138:139], v[236:237]
	v_lshlrev_b32_e32 v236, 16, v151
	v_and_b32_e32 v237, 0xffff0000, v151
	v_pk_fma_f32 v[120:121], v[120:121], v[140:141], v[236:237]
	v_lshlrev_b32_e32 v236, 16, v152
	v_and_b32_e32 v237, 0xffff0000, v152
	v_pk_fma_f32 v[114:115], v[114:115], v[142:143], v[236:237]
	v_lshlrev_b32_e32 v236, 16, v153
	v_and_b32_e32 v237, 0xffff0000, v153
	v_pk_fma_f32 v[116:117], v[116:117], v[144:145], v[236:237]
	v_lshlrev_b32_e32 v236, 16, v154
	v_and_b32_e32 v237, 0xffff0000, v154
	v_pk_fma_f32 v[108:109], v[108:109], v[130:131], v[236:237]
	v_lshlrev_b32_e32 v236, 16, v155
	v_and_b32_e32 v237, 0xffff0000, v155
	v_pk_fma_f32 v[110:111], v[110:111], v[132:133], v[236:237]
	v_lshlrev_b32_e32 v236, 16, v156
	v_and_b32_e32 v237, 0xffff0000, v156
	v_pk_fma_f32 v[104:105], v[104:105], v[134:135], v[236:237]
	v_lshlrev_b32_e32 v236, 16, v157
	v_and_b32_e32 v237, 0xffff0000, v157
	v_pk_fma_f32 v[106:107], v[106:107], v[136:137], v[236:237]
	v_lshlrev_b32_e32 v236, 16, v158
	v_and_b32_e32 v237, 0xffff0000, v158
	v_pk_fma_f32 v[100:101], v[100:101], v[138:139], v[236:237]
	v_lshlrev_b32_e32 v236, 16, v159
	v_and_b32_e32 v237, 0xffff0000, v159
	v_pk_fma_f32 v[102:103], v[102:103], v[140:141], v[236:237]
	v_lshlrev_b32_e32 v236, 16, v160
	v_and_b32_e32 v237, 0xffff0000, v160
	v_pk_fma_f32 v[96:97], v[96:97], v[142:143], v[236:237]
	v_lshlrev_b32_e32 v236, 16, v161
	v_and_b32_e32 v237, 0xffff0000, v161
	v_pk_fma_f32 v[98:99], v[98:99], v[144:145], v[236:237]
	v_lshlrev_b32_e32 v236, 16, v162
	v_and_b32_e32 v237, 0xffff0000, v162
	v_pk_fma_f32 v[92:93], v[92:93], v[130:131], v[236:237]
	v_lshlrev_b32_e32 v236, 16, v163
	v_and_b32_e32 v237, 0xffff0000, v163
	v_pk_fma_f32 v[94:95], v[94:95], v[132:133], v[236:237]
	v_lshlrev_b32_e32 v236, 16, v164
	v_and_b32_e32 v237, 0xffff0000, v164
	v_pk_fma_f32 v[88:89], v[88:89], v[134:135], v[236:237]
	v_lshlrev_b32_e32 v236, 16, v165
	v_and_b32_e32 v237, 0xffff0000, v165
	v_pk_fma_f32 v[90:91], v[90:91], v[136:137], v[236:237]
	v_lshlrev_b32_e32 v236, 16, v166
	v_and_b32_e32 v237, 0xffff0000, v166
	v_pk_fma_f32 v[84:85], v[84:85], v[138:139], v[236:237]
	v_lshlrev_b32_e32 v236, 16, v167
	v_and_b32_e32 v237, 0xffff0000, v167
	v_pk_fma_f32 v[86:87], v[86:87], v[140:141], v[236:237]
	v_lshlrev_b32_e32 v236, 16, v168
	v_and_b32_e32 v237, 0xffff0000, v168
	v_pk_fma_f32 v[80:81], v[80:81], v[142:143], v[236:237]
	v_lshlrev_b32_e32 v236, 16, v169
	v_and_b32_e32 v237, 0xffff0000, v169
	v_pk_fma_f32 v[82:83], v[82:83], v[144:145], v[236:237]
	v_lshlrev_b32_e32 v236, 16, v170
	v_and_b32_e32 v237, 0xffff0000, v170
	v_pk_fma_f32 v[76:77], v[76:77], v[130:131], v[236:237]
	v_lshlrev_b32_e32 v236, 16, v171
	v_and_b32_e32 v237, 0xffff0000, v171
	v_pk_fma_f32 v[78:79], v[78:79], v[132:133], v[236:237]
	v_lshlrev_b32_e32 v236, 16, v172
	v_and_b32_e32 v237, 0xffff0000, v172
	v_pk_fma_f32 v[72:73], v[72:73], v[134:135], v[236:237]
	v_lshlrev_b32_e32 v236, 16, v173
	v_and_b32_e32 v237, 0xffff0000, v173
	v_pk_fma_f32 v[74:75], v[74:75], v[136:137], v[236:237]
	v_lshlrev_b32_e32 v236, 16, v174
	v_and_b32_e32 v237, 0xffff0000, v174
	v_pk_fma_f32 v[68:69], v[68:69], v[138:139], v[236:237]
	v_lshlrev_b32_e32 v236, 16, v175
	v_and_b32_e32 v237, 0xffff0000, v175
	v_pk_fma_f32 v[70:71], v[70:71], v[140:141], v[236:237]
	v_lshlrev_b32_e32 v236, 16, v176
	v_and_b32_e32 v237, 0xffff0000, v176
	v_pk_fma_f32 v[64:65], v[64:65], v[142:143], v[236:237]
	v_lshlrev_b32_e32 v236, 16, v177
	v_and_b32_e32 v237, 0xffff0000, v177
	v_pk_fma_f32 v[66:67], v[66:67], v[144:145], v[236:237]
	v_mul_f32_e32 v236, v127, v127
	v_mul_f32_e32 v237, v129, v129
	v_fmac_f32_e32 v236, v126, v126
	v_fmac_f32_e32 v237, v128, v128
	v_add_f32_e32 v220, v236, v237
	v_mul_f32_e32 v236, v123, v123
	v_mul_f32_e32 v237, v125, v125
	v_fmac_f32_e32 v236, v122, v122
	v_fmac_f32_e32 v237, v124, v124
	v_add_f32_e32 v236, v236, v237
	v_add_f32_e32 v220, v236, v220
	v_mul_f32_e32 v236, v119, v119
	v_mul_f32_e32 v237, v121, v121
	v_fmac_f32_e32 v236, v118, v118
	v_fmac_f32_e32 v237, v120, v120
	v_add_f32_e32 v236, v236, v237
	v_add_f32_e32 v220, v236, v220
	v_mul_f32_e32 v236, v115, v115
	v_mul_f32_e32 v237, v117, v117
	v_fmac_f32_e32 v236, v114, v114
	v_fmac_f32_e32 v237, v116, v116
	v_add_f32_e32 v236, v236, v237
	v_add_f32_e32 v220, v236, v220
	v_mul_f32_e32 v236, v109, v109
	v_mul_f32_e32 v237, v111, v111
	v_fmac_f32_e32 v236, v108, v108
	v_fmac_f32_e32 v237, v110, v110
	v_add_f32_e32 v221, v236, v237
	v_mul_f32_e32 v236, v105, v105
	v_mul_f32_e32 v237, v107, v107
	v_fmac_f32_e32 v236, v104, v104
	v_fmac_f32_e32 v237, v106, v106
	v_add_f32_e32 v236, v236, v237
	v_add_f32_e32 v221, v236, v221
	v_mul_f32_e32 v236, v101, v101
	v_mul_f32_e32 v237, v103, v103
	v_fmac_f32_e32 v236, v100, v100
	v_fmac_f32_e32 v237, v102, v102
	v_add_f32_e32 v236, v236, v237
	v_add_f32_e32 v221, v236, v221
	v_mul_f32_e32 v236, v97, v97
	v_mul_f32_e32 v237, v99, v99
	v_fmac_f32_e32 v236, v96, v96
	v_fmac_f32_e32 v237, v98, v98
	v_add_f32_e32 v236, v236, v237
	v_add_f32_e32 v221, v236, v221
	v_mul_f32_e32 v236, v93, v93
	v_mul_f32_e32 v237, v95, v95
	v_fmac_f32_e32 v236, v92, v92
	v_fmac_f32_e32 v237, v94, v94
	v_add_f32_e32 v222, v236, v237
	v_mul_f32_e32 v236, v89, v89
	v_mul_f32_e32 v237, v91, v91
	v_fmac_f32_e32 v236, v88, v88
	v_fmac_f32_e32 v237, v90, v90
	v_add_f32_e32 v236, v236, v237
	v_add_f32_e32 v222, v236, v222
	v_mul_f32_e32 v236, v85, v85
	v_mul_f32_e32 v237, v87, v87
	v_fmac_f32_e32 v236, v84, v84
	v_fmac_f32_e32 v237, v86, v86
	v_add_f32_e32 v236, v236, v237
	v_add_f32_e32 v222, v236, v222
	v_mul_f32_e32 v236, v81, v81
	v_mul_f32_e32 v237, v83, v83
	v_fmac_f32_e32 v236, v80, v80
	v_fmac_f32_e32 v237, v82, v82
	v_add_f32_e32 v236, v236, v237
	v_add_f32_e32 v222, v236, v222
	v_mul_f32_e32 v236, v77, v77
	v_mul_f32_e32 v237, v79, v79
	v_fmac_f32_e32 v236, v76, v76
	v_fmac_f32_e32 v237, v78, v78
	v_add_f32_e32 v223, v236, v237
	v_mul_f32_e32 v236, v73, v73
	v_mul_f32_e32 v237, v75, v75
	v_fmac_f32_e32 v236, v72, v72
	v_fmac_f32_e32 v237, v74, v74
	v_add_f32_e32 v236, v236, v237
	v_add_f32_e32 v223, v236, v223
	v_mul_f32_e32 v236, v69, v69
	v_mul_f32_e32 v237, v71, v71
	v_fmac_f32_e32 v236, v68, v68
	v_fmac_f32_e32 v237, v70, v70
	v_add_f32_e32 v236, v236, v237
	v_add_f32_e32 v223, v236, v223
	v_mul_f32_e32 v236, v65, v65
	v_mul_f32_e32 v237, v67, v67
	v_fmac_f32_e32 v236, v64, v64
	v_fmac_f32_e32 v237, v66, v66
	v_add_f32_e32 v236, v236, v237
	v_add_f32_e32 v223, v236, v223
	ds_swizzle_b32 v228, v220 offset:swizzle(SWAP,16)
	ds_swizzle_b32 v229, v221 offset:swizzle(SWAP,16)
	ds_swizzle_b32 v230, v222 offset:swizzle(SWAP,16)
	ds_swizzle_b32 v231, v223 offset:swizzle(SWAP,16)
	s_waitcnt lgkmcnt(0)
	v_add_f32_e32 v220, v220, v228
	v_add_f32_e32 v221, v221, v229
	v_add_f32_e32 v222, v222, v230
	v_add_f32_e32 v223, v223, v231
	v_mov_b32_e32 v228, v220
	v_mov_b32_e32 v229, v221
	v_mov_b32_e32 v230, v222
	v_mov_b32_e32 v231, v223
	s_nop 1
	v_permlane32_swap_b32 v228, v220
	v_permlane32_swap_b32 v229, v221
	v_permlane32_swap_b32 v230, v222
	v_permlane32_swap_b32 v231, v223
	s_nop 1
	v_add_f32_e32 v220, v228, v220
	v_add_f32_e32 v221, v229, v221
	v_add_f32_e32 v222, v230, v222
	v_add_f32_e32 v223, v231, v223
	ds_write_b32 v214, v220 offset:0
	ds_write_b32 v214, v221 offset:256
	ds_write_b32 v214, v222 offset:512
	ds_write_b32 v214, v223 offset:768
	s_waitcnt vmcnt(0)
	v_lshlrev_b32_e32 v236, 16, v178
	v_and_b32_e32 v237, 0xffff0000, v178
	v_pk_fma_f32 v[60:61], v[60:61], v[130:131], v[236:237]
	v_lshlrev_b32_e32 v236, 16, v179
	v_and_b32_e32 v237, 0xffff0000, v179
	v_pk_fma_f32 v[62:63], v[62:63], v[132:133], v[236:237]
	v_lshlrev_b32_e32 v236, 16, v180
	v_and_b32_e32 v237, 0xffff0000, v180
	v_pk_fma_f32 v[56:57], v[56:57], v[134:135], v[236:237]
	v_lshlrev_b32_e32 v236, 16, v181
	v_and_b32_e32 v237, 0xffff0000, v181
	v_pk_fma_f32 v[58:59], v[58:59], v[136:137], v[236:237]
	v_lshlrev_b32_e32 v236, 16, v182
	v_and_b32_e32 v237, 0xffff0000, v182
	v_pk_fma_f32 v[52:53], v[52:53], v[138:139], v[236:237]
	v_lshlrev_b32_e32 v236, 16, v183
	v_and_b32_e32 v237, 0xffff0000, v183
	v_pk_fma_f32 v[54:55], v[54:55], v[140:141], v[236:237]
	v_lshlrev_b32_e32 v236, 16, v184
	v_and_b32_e32 v237, 0xffff0000, v184
	v_pk_fma_f32 v[48:49], v[48:49], v[142:143], v[236:237]
	v_lshlrev_b32_e32 v236, 16, v185
	v_and_b32_e32 v237, 0xffff0000, v185
	v_pk_fma_f32 v[50:51], v[50:51], v[144:145], v[236:237]
	v_lshlrev_b32_e32 v236, 16, v186
	v_and_b32_e32 v237, 0xffff0000, v186
	v_pk_fma_f32 v[44:45], v[44:45], v[130:131], v[236:237]
	v_lshlrev_b32_e32 v236, 16, v187
	v_and_b32_e32 v237, 0xffff0000, v187
	v_pk_fma_f32 v[46:47], v[46:47], v[132:133], v[236:237]
	v_lshlrev_b32_e32 v236, 16, v188
	v_and_b32_e32 v237, 0xffff0000, v188
	v_pk_fma_f32 v[40:41], v[40:41], v[134:135], v[236:237]
	v_lshlrev_b32_e32 v236, 16, v189
	v_and_b32_e32 v237, 0xffff0000, v189
	v_pk_fma_f32 v[42:43], v[42:43], v[136:137], v[236:237]
	v_lshlrev_b32_e32 v236, 16, v190
	v_and_b32_e32 v237, 0xffff0000, v190
	v_pk_fma_f32 v[36:37], v[36:37], v[138:139], v[236:237]
	v_lshlrev_b32_e32 v236, 16, v191
	v_and_b32_e32 v237, 0xffff0000, v191
	v_pk_fma_f32 v[38:39], v[38:39], v[140:141], v[236:237]
	v_lshlrev_b32_e32 v236, 16, v192
	v_and_b32_e32 v237, 0xffff0000, v192
	v_pk_fma_f32 v[32:33], v[32:33], v[142:143], v[236:237]
	v_lshlrev_b32_e32 v236, 16, v193
	v_and_b32_e32 v237, 0xffff0000, v193
	v_pk_fma_f32 v[34:35], v[34:35], v[144:145], v[236:237]
	v_lshlrev_b32_e32 v236, 16, v194
	v_and_b32_e32 v237, 0xffff0000, v194
	v_pk_fma_f32 v[28:29], v[28:29], v[130:131], v[236:237]
	v_lshlrev_b32_e32 v236, 16, v195
	v_and_b32_e32 v237, 0xffff0000, v195
	v_pk_fma_f32 v[30:31], v[30:31], v[132:133], v[236:237]
	v_lshlrev_b32_e32 v236, 16, v196
	v_and_b32_e32 v237, 0xffff0000, v196
	v_pk_fma_f32 v[24:25], v[24:25], v[134:135], v[236:237]
	v_lshlrev_b32_e32 v236, 16, v197
	v_and_b32_e32 v237, 0xffff0000, v197
	v_pk_fma_f32 v[26:27], v[26:27], v[136:137], v[236:237]
	v_lshlrev_b32_e32 v236, 16, v198
	v_and_b32_e32 v237, 0xffff0000, v198
	v_pk_fma_f32 v[20:21], v[20:21], v[138:139], v[236:237]
	v_lshlrev_b32_e32 v236, 16, v199
	v_and_b32_e32 v237, 0xffff0000, v199
	v_pk_fma_f32 v[22:23], v[22:23], v[140:141], v[236:237]
	v_lshlrev_b32_e32 v236, 16, v200
	v_and_b32_e32 v237, 0xffff0000, v200
	v_pk_fma_f32 v[16:17], v[16:17], v[142:143], v[236:237]
	v_lshlrev_b32_e32 v236, 16, v201
	v_and_b32_e32 v237, 0xffff0000, v201
	v_pk_fma_f32 v[18:19], v[18:19], v[144:145], v[236:237]
	v_lshlrev_b32_e32 v236, 16, v202
	v_and_b32_e32 v237, 0xffff0000, v202
	v_pk_fma_f32 v[12:13], v[12:13], v[130:131], v[236:237]
	v_lshlrev_b32_e32 v236, 16, v203
	v_and_b32_e32 v237, 0xffff0000, v203
	v_pk_fma_f32 v[14:15], v[14:15], v[132:133], v[236:237]
	v_lshlrev_b32_e32 v236, 16, v204
	v_and_b32_e32 v237, 0xffff0000, v204
	v_pk_fma_f32 v[4:5], v[4:5], v[134:135], v[236:237]
	v_lshlrev_b32_e32 v236, 16, v205
	v_and_b32_e32 v237, 0xffff0000, v205
	v_pk_fma_f32 v[6:7], v[6:7], v[136:137], v[236:237]
	v_lshlrev_b32_e32 v236, 16, v206
	v_and_b32_e32 v237, 0xffff0000, v206
	v_pk_fma_f32 v[8:9], v[8:9], v[138:139], v[236:237]
	v_lshlrev_b32_e32 v236, 16, v207
	v_and_b32_e32 v237, 0xffff0000, v207
	v_pk_fma_f32 v[10:11], v[10:11], v[140:141], v[236:237]
	v_lshlrev_b32_e32 v236, 16, v208
	v_and_b32_e32 v237, 0xffff0000, v208
	v_pk_fma_f32 v[0:1], v[0:1], v[142:143], v[236:237]
	v_lshlrev_b32_e32 v236, 16, v209
	v_and_b32_e32 v237, 0xffff0000, v209
	v_pk_fma_f32 v[2:3], v[2:3], v[144:145], v[236:237]
	v_mul_f32_e32 v236, v61, v61
	v_mul_f32_e32 v237, v63, v63
	v_fmac_f32_e32 v236, v60, v60
	v_fmac_f32_e32 v237, v62, v62
	v_add_f32_e32 v224, v236, v237
	v_mul_f32_e32 v236, v57, v57
	v_mul_f32_e32 v237, v59, v59
	v_fmac_f32_e32 v236, v56, v56
	v_fmac_f32_e32 v237, v58, v58
	v_add_f32_e32 v236, v236, v237
	v_add_f32_e32 v224, v236, v224
	v_mul_f32_e32 v236, v53, v53
	v_mul_f32_e32 v237, v55, v55
	v_fmac_f32_e32 v236, v52, v52
	v_fmac_f32_e32 v237, v54, v54
	v_add_f32_e32 v236, v236, v237
	v_add_f32_e32 v224, v236, v224
	v_mul_f32_e32 v236, v49, v49
	v_mul_f32_e32 v237, v51, v51
	v_fmac_f32_e32 v236, v48, v48
	v_fmac_f32_e32 v237, v50, v50
	v_add_f32_e32 v236, v236, v237
	v_add_f32_e32 v224, v236, v224
	v_mul_f32_e32 v236, v45, v45
	v_mul_f32_e32 v237, v47, v47
	v_fmac_f32_e32 v236, v44, v44
	v_fmac_f32_e32 v237, v46, v46
	v_add_f32_e32 v225, v236, v237
	v_mul_f32_e32 v236, v41, v41
	v_mul_f32_e32 v237, v43, v43
	v_fmac_f32_e32 v236, v40, v40
	v_fmac_f32_e32 v237, v42, v42
	v_add_f32_e32 v236, v236, v237
	v_add_f32_e32 v225, v236, v225
	v_mul_f32_e32 v236, v37, v37
	v_mul_f32_e32 v237, v39, v39
	v_fmac_f32_e32 v236, v36, v36
	v_fmac_f32_e32 v237, v38, v38
	v_add_f32_e32 v236, v236, v237
	v_add_f32_e32 v225, v236, v225
	v_mul_f32_e32 v236, v33, v33
	v_mul_f32_e32 v237, v35, v35
	v_fmac_f32_e32 v236, v32, v32
	v_fmac_f32_e32 v237, v34, v34
	v_add_f32_e32 v236, v236, v237
	v_add_f32_e32 v225, v236, v225
	v_mul_f32_e32 v236, v29, v29
	v_mul_f32_e32 v237, v31, v31
	v_fmac_f32_e32 v236, v28, v28
	v_fmac_f32_e32 v237, v30, v30
	v_add_f32_e32 v226, v236, v237
	v_mul_f32_e32 v236, v25, v25
	v_mul_f32_e32 v237, v27, v27
	v_fmac_f32_e32 v236, v24, v24
	v_fmac_f32_e32 v237, v26, v26
	v_add_f32_e32 v236, v236, v237
	v_add_f32_e32 v226, v236, v226
	v_mul_f32_e32 v236, v21, v21
	v_mul_f32_e32 v237, v23, v23
	v_fmac_f32_e32 v236, v20, v20
	v_fmac_f32_e32 v237, v22, v22
	v_add_f32_e32 v236, v236, v237
	v_add_f32_e32 v226, v236, v226
	v_mul_f32_e32 v236, v17, v17
	v_mul_f32_e32 v237, v19, v19
	v_fmac_f32_e32 v236, v16, v16
	v_fmac_f32_e32 v237, v18, v18
	v_add_f32_e32 v236, v236, v237
	v_add_f32_e32 v226, v236, v226
	v_mul_f32_e32 v236, v13, v13
	v_mul_f32_e32 v237, v15, v15
	v_fmac_f32_e32 v236, v12, v12
	v_fmac_f32_e32 v237, v14, v14
	v_add_f32_e32 v227, v236, v237
	v_mul_f32_e32 v236, v5, v5
	v_mul_f32_e32 v237, v7, v7
	v_fmac_f32_e32 v236, v4, v4
	v_fmac_f32_e32 v237, v6, v6
	v_add_f32_e32 v236, v236, v237
	v_add_f32_e32 v227, v236, v227
	v_mul_f32_e32 v236, v9, v9
	v_mul_f32_e32 v237, v11, v11
	v_fmac_f32_e32 v236, v8, v8
	v_fmac_f32_e32 v237, v10, v10
	v_add_f32_e32 v236, v236, v237
	v_add_f32_e32 v227, v236, v227
	v_mul_f32_e32 v236, v1, v1
	v_mul_f32_e32 v237, v3, v3
	v_fmac_f32_e32 v236, v0, v0
	v_fmac_f32_e32 v237, v2, v2
	v_add_f32_e32 v236, v236, v237
	v_add_f32_e32 v227, v236, v227
	ds_swizzle_b32 v232, v224 offset:swizzle(SWAP,16)
	ds_swizzle_b32 v233, v225 offset:swizzle(SWAP,16)
	ds_swizzle_b32 v234, v226 offset:swizzle(SWAP,16)
	ds_swizzle_b32 v235, v227 offset:swizzle(SWAP,16)
	s_waitcnt lgkmcnt(0)
	v_add_f32_e32 v224, v224, v232
	v_add_f32_e32 v225, v225, v233
	v_add_f32_e32 v226, v226, v234
	v_add_f32_e32 v227, v227, v235
	v_mov_b32_e32 v232, v224
	v_mov_b32_e32 v233, v225
	v_mov_b32_e32 v234, v226
	v_mov_b32_e32 v235, v227
	s_nop 1
	v_permlane32_swap_b32 v232, v224
	v_permlane32_swap_b32 v233, v225
	v_permlane32_swap_b32 v234, v226
	v_permlane32_swap_b32 v235, v227
	s_nop 1
	v_add_f32_e32 v224, v232, v224
	v_add_f32_e32 v225, v233, v225
	v_add_f32_e32 v226, v234, v226
	v_add_f32_e32 v227, v235, v227
	ds_write_b32 v214, v224 offset:2048
	ds_write_b32 v214, v225 offset:2304
	ds_write_b32 v214, v226 offset:2560
	ds_write_b32 v214, v227 offset:2816
	s_cmp_eq_u32 s60, 3
	s_cbranch_scc1 .Lo4_tail_last
	s_branch .Lo4_tail_next
.Lo4_first:
	s_load_dwordx4 s[28:31], s[0:1], 0x0
	s_lshl_b32 s41, s39, 12
	s_add_u32 s41, s41, s40
	s_cmp_lt_u32 s34, 32
	s_waitcnt lgkmcnt(0)
	s_cbranch_scc1 .Lo4_prompt
	s_sub_u32 s41, s41, 0x2000000
	s_mov_b64 s[28:29], s[30:31]
.Lo4_prompt:
	s_add_u32 s6, s28, s41
	s_addc_u32 s7, s29, 0
	global_load_dwordx4 v[130:133], v210, s[10:11] offset:0
	global_load_dwordx4 v[134:137], v210, s[10:11] offset:16
	global_load_dwordx4 v[138:141], v210, s[10:11] offset:512
	global_load_dwordx4 v[142:145], v210, s[10:11] offset:528
	s_mov_b64 s[28:29], s[6:7]
	s_mov_b64 s[30:31], s[6:7]
	global_load_dwordx4 v[146:149], v211, s[28:29] offset:0
	global_load_dwordx4 v[150:153], v211, s[28:29] offset:16
	s_add_u32 s28, s28, 0x10000
	s_addc_u32 s29, s29, 0
	global_load_dwordx4 v[154:157], v211, s[28:29] offset:0
	global_load_dwordx4 v[158:161], v211, s[28:29] offset:16
	s_add_u32 s28, s28, 0x10000
	s_addc_u32 s29, s29, 0
	global_load_dwordx4 v[162:165], v211, s[28:29] offset:0
	global_load_dwordx4 v[166:169], v211, s[28:29] offset:16
	s_add_u32 s28, s28, 0x10000
	s_addc_u32 s29, s29, 0
	global_load_dwordx4 v[170:173], v211, s[28:29] offset:0
	global_load_dwordx4 v[174:177], v211, s[28:29] offset:16
	s_add_u32 s28, s28, 0x50000
	s_addc_u32 s29, s29, 0
	global_load_dwordx4 v[178:181], v211, s[30:31] offset:512
	global_load_dwordx4 v[182:185], v211, s[30:31] offset:528
	s_add_u32 s30, s30, 0x10000
	s_addc_u32 s31, s31, 0
	global_load_dwordx4 v[186:189], v211, s[30:31] offset:512
	global_load_dwordx4 v[190:193], v211, s[30:31] offset:528
	s_add_u32 s30, s30, 0x10000
	s_addc_u32 s31, s31, 0
	global_load_dwordx4 v[194:197], v211, s[30:31] offset:512
	global_load_dwordx4 v[198:201], v211, s[30:31] offset:528
	s_add_u32 s30, s30, 0x10000
	s_addc_u32 s31, s31, 0
	global_load_dwordx4 v[202:205], v211, s[30:31] offset:512
	global_load_dwordx4 v[206:209], v211, s[30:31] offset:528
	s_add_u32 s30, s30, 0x50000
	s_addc_u32 s31, s31, 0
	s_waitcnt vmcnt(8)
	v_pk_fma_f32 v[126:127], v[126:127], v[130:131], v[146:147]
	v_pk_fma_f32 v[128:129], v[128:129], v[132:133], v[148:149]
	v_pk_fma_f32 v[122:123], v[122:123], v[134:135], v[150:151]
	v_pk_fma_f32 v[124:125], v[124:125], v[136:137], v[152:153]
	v_pk_fma_f32 v[108:109], v[108:109], v[130:131], v[154:155]
	v_pk_fma_f32 v[110:111], v[110:111], v[132:133], v[156:157]
	v_pk_fma_f32 v[104:105], v[104:105], v[134:135], v[158:159]
	v_pk_fma_f32 v[106:107], v[106:107], v[136:137], v[160:161]
	v_pk_fma_f32 v[92:93], v[92:93], v[130:131], v[162:163]
	v_pk_fma_f32 v[94:95], v[94:95], v[132:133], v[164:165]
	v_pk_fma_f32 v[88:89], v[88:89], v[134:135], v[166:167]
	v_pk_fma_f32 v[90:91], v[90:91], v[136:137], v[168:169]
	v_pk_fma_f32 v[76:77], v[76:77], v[130:131], v[170:171]
	v_pk_fma_f32 v[78:79], v[78:79], v[132:133], v[172:173]
	v_pk_fma_f32 v[72:73], v[72:73], v[134:135], v[174:175]
	v_pk_fma_f32 v[74:75], v[74:75], v[136:137], v[176:177]
	global_load_dwordx4 v[146:149], v211, s[28:29] offset:0
	global_load_dwordx4 v[150:153], v211, s[28:29] offset:16
	s_add_u32 s28, s28, 0x10000
	s_addc_u32 s29, s29, 0
	global_load_dwordx4 v[154:157], v211, s[28:29] offset:0
	global_load_dwordx4 v[158:161], v211, s[28:29] offset:16
	s_add_u32 s28, s28, 0x10000
	s_addc_u32 s29, s29, 0
	global_load_dwordx4 v[162:165], v211, s[28:29] offset:0
	global_load_dwordx4 v[166:169], v211, s[28:29] offset:16
	s_add_u32 s28, s28, 0x10000
	s_addc_u32 s29, s29, 0
	global_load_dwordx4 v[170:173], v211, s[28:29] offset:0
	global_load_dwordx4 v[174:177], v211, s[28:29] offset:16
	s_add_u32 s28, s28, 0x50000
	s_addc_u32 s29, s29, 0
	s_waitcnt vmcnt(8)
	v_pk_fma_f32 v[118:119], v[118:119], v[138:139], v[178:179]
	v_pk_fma_f32 v[120:121], v[120:121], v[140:141], v[180:181]
	v_pk_fma_f32 v[114:115], v[114:115], v[142:143], v[182:183]
	v_pk_fma_f32 v[116:117], v[116:117], v[144:145], v[184:185]
	v_pk_fma_f32 v[100:101], v[100:101], v[138:139], v[186:187]
	v_pk_fma_f32 v[102:103], v[102:103], v[140:141], v[188:189]
	v_pk_fma_f32 v[96:97], v[96:97], v[142:143], v[190:191]
	v_pk_fma_f32 v[98:99], v[98:99], v[144:145], v[192:193]
	v_pk_fma_f32 v[84:85], v[84:85], v[138:139], v[194:195]
	v_pk_fma_f32 v[86:87], v[86:87], v[140:141], v[196:197]
	v_pk_fma_f32 v[80:81], v[80:81], v[142:143], v[198:199]
	v_pk_fma_f32 v[82:83], v[82:83], v[144:145], v[200:201]
	v_pk_fma_f32 v[68:69], v[68:69], v[138:139], v[202:203]
	v_pk_fma_f32 v[70:71], v[70:71], v[140:141], v[204:205]
	v_pk_fma_f32 v[64:65], v[64:65], v[142:143], v[206:207]
	v_pk_fma_f32 v[66:67], v[66:67], v[144:145], v[208:209]
	global_load_dwordx4 v[178:181], v211, s[30:31] offset:512
	global_load_dwordx4 v[182:185], v211, s[30:31] offset:528
	s_add_u32 s30, s30, 0x10000
	s_addc_u32 s31, s31, 0
	global_load_dwordx4 v[186:189], v211, s[30:31] offset:512
	global_load_dwordx4 v[190:193], v211, s[30:31] offset:528
	s_add_u32 s30, s30, 0x10000
	s_addc_u32 s31, s31, 0
	global_load_dwordx4 v[194:197], v211, s[30:31] offset:512
	global_load_dwordx4 v[198:201], v211, s[30:31] offset:528
	s_add_u32 s30, s30, 0x10000
	s_addc_u32 s31, s31, 0
	global_load_dwordx4 v[202:205], v211, s[30:31] offset:512
	global_load_dwordx4 v[206:209], v211, s[30:31] offset:528
	s_add_u32 s30, s30, 0x50000
	s_addc_u32 s31, s31, 0
	v_mul_f32_e32 v236, v127, v127
	v_mul_f32_e32 v237, v129, v129
	v_fmac_f32_e32 v236, v126, v126
	v_fmac_f32_e32 v237, v128, v128
	v_add_f32_e32 v220, v236, v237
	v_mul_f32_e32 v236, v123, v123
	v_mul_f32_e32 v237, v125, v125
	v_fmac_f32_e32 v236, v122, v122
	v_fmac_f32_e32 v237, v124, v124
	v_add_f32_e32 v236, v236, v237
	v_add_f32_e32 v220, v236, v220
	v_mul_f32_e32 v236, v119, v119
	v_mul_f32_e32 v237, v121, v121
	v_fmac_f32_e32 v236, v118, v118
	v_fmac_f32_e32 v237, v120, v120
	v_add_f32_e32 v236, v236, v237
	v_add_f32_e32 v220, v236, v220
	v_mul_f32_e32 v236, v115, v115
	v_mul_f32_e32 v237, v117, v117
	v_fmac_f32_e32 v236, v114, v114
	v_fmac_f32_e32 v237, v116, v116
	v_add_f32_e32 v236, v236, v237
	v_add_f32_e32 v220, v236, v220
	v_mul_f32_e32 v236, v109, v109
	v_mul_f32_e32 v237, v111, v111
	v_fmac_f32_e32 v236, v108, v108
	v_fmac_f32_e32 v237, v110, v110
	v_add_f32_e32 v221, v236, v237
	v_mul_f32_e32 v236, v105, v105
	v_mul_f32_e32 v237, v107, v107
	v_fmac_f32_e32 v236, v104, v104
	v_fmac_f32_e32 v237, v106, v106
	v_add_f32_e32 v236, v236, v237
	v_add_f32_e32 v221, v236, v221
	v_mul_f32_e32 v236, v101, v101
	v_mul_f32_e32 v237, v103, v103
	v_fmac_f32_e32 v236, v100, v100
	v_fmac_f32_e32 v237, v102, v102
	v_add_f32_e32 v236, v236, v237
	v_add_f32_e32 v221, v236, v221
	v_mul_f32_e32 v236, v97, v97
	v_mul_f32_e32 v237, v99, v99
	v_fmac_f32_e32 v236, v96, v96
	v_fmac_f32_e32 v237, v98, v98
	v_add_f32_e32 v236, v236, v237
	v_add_f32_e32 v221, v236, v221
	v_mul_f32_e32 v236, v93, v93
	v_mul_f32_e32 v237, v95, v95
	v_fmac_f32_e32 v236, v92, v92
	v_fmac_f32_e32 v237, v94, v94
	v_add_f32_e32 v222, v236, v237
	v_mul_f32_e32 v236, v89, v89
	v_mul_f32_e32 v237, v91, v91
	v_fmac_f32_e32 v236, v88, v88
	v_fmac_f32_e32 v237, v90, v90
	v_add_f32_e32 v236, v236, v237
	v_add_f32_e32 v222, v236, v222
	v_mul_f32_e32 v236, v85, v85
	v_mul_f32_e32 v237, v87, v87
	v_fmac_f32_e32 v236, v84, v84
	v_fmac_f32_e32 v237, v86, v86
	v_add_f32_e32 v236, v236, v237
	v_add_f32_e32 v222, v236, v222
	v_mul_f32_e32 v236, v81, v81
	v_mul_f32_e32 v237, v83, v83
	v_fmac_f32_e32 v236, v80, v80
	v_fmac_f32_e32 v237, v82, v82
	v_add_f32_e32 v236, v236, v237
	v_add_f32_e32 v222, v236, v222
	v_mul_f32_e32 v236, v77, v77
	v_mul_f32_e32 v237, v79, v79
	v_fmac_f32_e32 v236, v76, v76
	v_fmac_f32_e32 v237, v78, v78
	v_add_f32_e32 v223, v236, v237
	v_mul_f32_e32 v236, v73, v73
	v_mul_f32_e32 v237, v75, v75
	v_fmac_f32_e32 v236, v72, v72
	v_fmac_f32_e32 v237, v74, v74
	v_add_f32_e32 v236, v236, v237
	v_add_f32_e32 v223, v236, v223
	v_mul_f32_e32 v236, v69, v69
	v_mul_f32_e32 v237, v71, v71
	v_fmac_f32_e32 v236, v68, v68
	v_fmac_f32_e32 v237, v70, v70
	v_add_f32_e32 v236, v236, v237
	v_add_f32_e32 v223, v236, v223
	v_mul_f32_e32 v236, v65, v65
	v_mul_f32_e32 v237, v67, v67
	v_fmac_f32_e32 v236, v64, v64
	v_fmac_f32_e32 v237, v66, v66
	v_add_f32_e32 v236, v236, v237
	v_add_f32_e32 v223, v236, v223
	ds_swizzle_b32 v228, v220 offset:swizzle(SWAP,16)
	ds_swizzle_b32 v229, v221 offset:swizzle(SWAP,16)
	ds_swizzle_b32 v230, v222 offset:swizzle(SWAP,16)
	ds_swizzle_b32 v231, v223 offset:swizzle(SWAP,16)
	s_waitcnt lgkmcnt(0)
	v_add_f32_e32 v220, v220, v228
	v_add_f32_e32 v221, v221, v229
	v_add_f32_e32 v222, v222, v230
	v_add_f32_e32 v223, v223, v231
	v_mov_b32_e32 v228, v220
	v_mov_b32_e32 v229, v221
	v_mov_b32_e32 v230, v222
	v_mov_b32_e32 v231, v223
	s_nop 1
	v_permlane32_swap_b32 v228, v220
	v_permlane32_swap_b32 v229, v221
	v_permlane32_swap_b32 v230, v222
	v_permlane32_swap_b32 v231, v223
	s_nop 1
	v_add_f32_e32 v220, v228, v220
	v_add_f32_e32 v221, v229, v221
	v_add_f32_e32 v222, v230, v222
	v_add_f32_e32 v223, v231, v223
	ds_write_b32 v214, v220 offset:0
	ds_write_b32 v214, v221 offset:256
	ds_write_b32 v214, v222 offset:512
	ds_write_b32 v214, v223 offset:768
	s_waitcnt vmcnt(8)
	v_pk_fma_f32 v[60:61], v[60:61], v[130:131], v[146:147]
	v_pk_fma_f32 v[62:63], v[62:63], v[132:133], v[148:149]
	v_pk_fma_f32 v[56:57], v[56:57], v[134:135], v[150:151]
	v_pk_fma_f32 v[58:59], v[58:59], v[136:137], v[152:153]
	v_pk_fma_f32 v[44:45], v[44:45], v[130:131], v[154:155]
	v_pk_fma_f32 v[46:47], v[46:47], v[132:133], v[156:157]
	v_pk_fma_f32 v[40:41], v[40:41], v[134:135], v[158:159]
	v_pk_fma_f32 v[42:43], v[42:43], v[136:137], v[160:161]
	v_pk_fma_f32 v[28:29], v[28:29], v[130:131], v[162:163]
	v_pk_fma_f32 v[30:31], v[30:31], v[132:133], v[164:165]
	v_pk_fma_f32 v[24:25], v[24:25], v[134:135], v[166:167]
	v_pk_fma_f32 v[26:27], v[26:27], v[136:137], v[168:169]
	v_pk_fma_f32 v[12:13], v[12:13], v[130:131], v[170:171]
	v_pk_fma_f32 v[14:15], v[14:15], v[132:133], v[172:173]
	v_pk_fma_f32 v[4:5], v[4:5], v[134:135], v[174:175]
	v_pk_fma_f32 v[6:7], v[6:7], v[136:137], v[176:177]
	s_waitcnt vmcnt(0)
	v_pk_fma_f32 v[52:53], v[52:53], v[138:139], v[178:179]
	v_pk_fma_f32 v[54:55], v[54:55], v[140:141], v[180:181]
	v_pk_fma_f32 v[48:49], v[48:49], v[142:143], v[182:183]
	v_pk_fma_f32 v[50:51], v[50:51], v[144:145], v[184:185]
	v_pk_fma_f32 v[36:37], v[36:37], v[138:139], v[186:187]
	v_pk_fma_f32 v[38:39], v[38:39], v[140:141], v[188:189]
	v_pk_fma_f32 v[32:33], v[32:33], v[142:143], v[190:191]
	v_pk_fma_f32 v[34:35], v[34:35], v[144:145], v[192:193]
	v_pk_fma_f32 v[20:21], v[20:21], v[138:139], v[194:195]
	v_pk_fma_f32 v[22:23], v[22:23], v[140:141], v[196:197]
	v_pk_fma_f32 v[16:17], v[16:17], v[142:143], v[198:199]
	v_pk_fma_f32 v[18:19], v[18:19], v[144:145], v[200:201]
	v_pk_fma_f32 v[8:9], v[8:9], v[138:139], v[202:203]
	v_pk_fma_f32 v[10:11], v[10:11], v[140:141], v[204:205]
	v_pk_fma_f32 v[0:1], v[0:1], v[142:143], v[206:207]
	v_pk_fma_f32 v[2:3], v[2:3], v[144:145], v[208:209]
	v_mul_f32_e32 v236, v61, v61
	v_mul_f32_e32 v237, v63, v63
	v_fmac_f32_e32 v236, v60, v60
	v_fmac_f32_e32 v237, v62, v62
	v_add_f32_e32 v224, v236, v237
	v_mul_f32_e32 v236, v57, v57
	v_mul_f32_e32 v237, v59, v59
	v_fmac_f32_e32 v236, v56, v56
	v_fmac_f32_e32 v237, v58, v58
	v_add_f32_e32 v236, v236, v237
	v_add_f32_e32 v224, v236, v224
	v_mul_f32_e32 v236, v53, v53
	v_mul_f32_e32 v237, v55, v55
	v_fmac_f32_e32 v236, v52, v52
	v_fmac_f32_e32 v237, v54, v54
	v_add_f32_e32 v236, v236, v237
	v_add_f32_e32 v224, v236, v224
	v_mul_f32_e32 v236, v49, v49
	v_mul_f32_e32 v237, v51, v51
	v_fmac_f32_e32 v236, v48, v48
	v_fmac_f32_e32 v237, v50, v50
	v_add_f32_e32 v236, v236, v237
	v_add_f32_e32 v224, v236, v224
	v_mul_f32_e32 v236, v45, v45
	v_mul_f32_e32 v237, v47, v47
	v_fmac_f32_e32 v236, v44, v44
	v_fmac_f32_e32 v237, v46, v46
	v_add_f32_e32 v225, v236, v237
	v_mul_f32_e32 v236, v41, v41
	v_mul_f32_e32 v237, v43, v43
	v_fmac_f32_e32 v236, v40, v40
	v_fmac_f32_e32 v237, v42, v42
	v_add_f32_e32 v236, v236, v237
	v_add_f32_e32 v225, v236, v225
	v_mul_f32_e32 v236, v37, v37
	v_mul_f32_e32 v237, v39, v39
	v_fmac_f32_e32 v236, v36, v36
	v_fmac_f32_e32 v237, v38, v38
	v_add_f32_e32 v236, v236, v237
	v_add_f32_e32 v225, v236, v225
	v_mul_f32_e32 v236, v33, v33
	v_mul_f32_e32 v237, v35, v35
	v_fmac_f32_e32 v236, v32, v32
	v_fmac_f32_e32 v237, v34, v34
	v_add_f32_e32 v236, v236, v237
	v_add_f32_e32 v225, v236, v225
	v_mul_f32_e32 v236, v29, v29
	v_mul_f32_e32 v237, v31, v31
	v_fmac_f32_e32 v236, v28, v28
	v_fmac_f32_e32 v237, v30, v30
	v_add_f32_e32 v226, v236, v237
	v_mul_f32_e32 v236, v25, v25
	v_mul_f32_e32 v237, v27, v27
	v_fmac_f32_e32 v236, v24, v24
	v_fmac_f32_e32 v237, v26, v26
	v_add_f32_e32 v236, v236, v237
	v_add_f32_e32 v226, v236, v226
	v_mul_f32_e32 v236, v21, v21
	v_mul_f32_e32 v237, v23, v23
	v_fmac_f32_e32 v236, v20, v20
	v_fmac_f32_e32 v237, v22, v22
	v_add_f32_e32 v236, v236, v237
	v_add_f32_e32 v226, v236, v226
	v_mul_f32_e32 v236, v17, v17
	v_mul_f32_e32 v237, v19, v19
	v_fmac_f32_e32 v236, v16, v16
	v_fmac_f32_e32 v237, v18, v18
	v_add_f32_e32 v236, v236, v237
	v_add_f32_e32 v226, v236, v226
	v_mul_f32_e32 v236, v13, v13
	v_mul_f32_e32 v237, v15, v15
	v_fmac_f32_e32 v236, v12, v12
	v_fmac_f32_e32 v237, v14, v14
	v_add_f32_e32 v227, v236, v237
	v_mul_f32_e32 v236, v5, v5
	v_mul_f32_e32 v237, v7, v7
	v_fmac_f32_e32 v236, v4, v4
	v_fmac_f32_e32 v237, v6, v6
	v_add_f32_e32 v236, v236, v237
	v_add_f32_e32 v227, v236, v227
	v_mul_f32_e32 v236, v9, v9
	v_mul_f32_e32 v237, v11, v11
	v_fmac_f32_e32 v236, v8, v8
	v_fmac_f32_e32 v237, v10, v10
	v_add_f32_e32 v236, v236, v237
	v_add_f32_e32 v227, v236, v227
	v_mul_f32_e32 v236, v1, v1
	v_mul_f32_e32 v237, v3, v3
	v_fmac_f32_e32 v236, v0, v0
	v_fmac_f32_e32 v237, v2, v2
	v_add_f32_e32 v236, v236, v237
	v_add_f32_e32 v227, v236, v227
	ds_swizzle_b32 v232, v224 offset:swizzle(SWAP,16)
	ds_swizzle_b32 v233, v225 offset:swizzle(SWAP,16)
	ds_swizzle_b32 v234, v226 offset:swizzle(SWAP,16)
	ds_swizzle_b32 v235, v227 offset:swizzle(SWAP,16)
	s_waitcnt lgkmcnt(0)
	v_add_f32_e32 v224, v224, v232
	v_add_f32_e32 v225, v225, v233
	v_add_f32_e32 v226, v226, v234
	v_add_f32_e32 v227, v227, v235
	v_mov_b32_e32 v232, v224
	v_mov_b32_e32 v233, v225
	v_mov_b32_e32 v234, v226
	v_mov_b32_e32 v235, v227
	s_nop 1
	v_permlane32_swap_b32 v232, v224
	v_permlane32_swap_b32 v233, v225
	v_permlane32_swap_b32 v234, v226
	v_permlane32_swap_b32 v235, v227
	s_nop 1
	v_add_f32_e32 v224, v232, v224
	v_add_f32_e32 v225, v233, v225
	v_add_f32_e32 v226, v234, v226
	v_add_f32_e32 v227, v235, v227
	ds_write_b32 v214, v224 offset:2048
	ds_write_b32 v214, v225 offset:2304
	ds_write_b32 v214, v226 offset:2560
	ds_write_b32 v214, v227 offset:2816
	s_lshl_b32 s41, s39, 12
	s_lshl_b32 s28, s74, 10
	s_add_u32 s41, s41, s28
	s_lshl_b32 s28, s35, 1
	s_add_u32 s41, s41, s28
	s_add_u32 s41, s41, 0xb0000
	s_add_u32 s6, s4, s41
	s_addc_u32 s7, s5, 0
.Lo4_tail_next:
	global_load_dwordx4 v[146:149], v210, s[20:21] offset:0
	global_load_dwordx4 v[150:153], v210, s[20:21] offset:16
	global_load_dwordx4 v[154:157], v210, s[20:21] offset:512
	global_load_dwordx4 v[158:161], v210, s[20:21] offset:528
	global_load_dwordx4 v[178:181], v210, s[12:13] offset:0
	global_load_dwordx4 v[182:185], v210, s[12:13] offset:16
	global_load_dwordx4 v[186:189], v210, s[12:13] offset:512
	global_load_dwordx4 v[190:193], v210, s[12:13] offset:528
	s_add_u32 s28, s12, 0x1000
	s_addc_u32 s29, s13, 0
	global_load_dwordx4 v[162:165], v210, s[28:29] offset:0
	global_load_dwordx4 v[166:169], v210, s[28:29] offset:16
	global_load_dwordx4 v[170:173], v210, s[28:29] offset:512
	global_load_dwordx4 v[174:177], v210, s[28:29] offset:528
	s_waitcnt lgkmcnt(0)
	s_barrier
	s_lshl_b32 s28, s74, 2
	s_add_u32 s28, s22, s28
	s_addc_u32 s29, s23, 0
	s_mov_b32 exec_lo, -1
	s_mov_b32 exec_hi, 0
	ds_read_b128 v[236:239], v215
	s_waitcnt lgkmcnt(0)
	v_add_f32_e32 v236, v236, v237
	v_add_f32_e32 v238, v238, v239
	v_add_f32_e32 v236, v236, v238
	global_store_dword v215, v236, s[28:29] sc1
	s_mov_b64 exec, -1
	s_waitcnt vmcnt(0)
	s_mov_b64 exec, 1
	global_atomic_add v113, v246, s[24:25]
	s_mov_b64 exec, -1
	s_sub_u32 s6, s6, 0xb0000
	s_subb_u32 s7, s7, 0
	v_cvt_pk_bf16_f32 v202, v126, v127
	v_cvt_pk_bf16_f32 v203, v128, v129
	v_cvt_pk_bf16_f32 v204, v122, v123
	v_cvt_pk_bf16_f32 v205, v124, v125
	global_store_dwordx4 v212, v[202:205], s[6:7]
	v_cvt_pk_bf16_f32 v206, v118, v119
	v_cvt_pk_bf16_f32 v207, v120, v121
	v_cvt_pk_bf16_f32 v208, v114, v115
	v_cvt_pk_bf16_f32 v209, v116, v117
	global_store_dwordx4 v212, v[206:209], s[6:7] offset:256
	s_add_u32 s6, s6, 0x10000
	s_addc_u32 s7, s7, 0
	v_cvt_pk_bf16_f32 v202, v108, v109
	v_cvt_pk_bf16_f32 v203, v110, v111
	v_cvt_pk_bf16_f32 v204, v104, v105
	v_cvt_pk_bf16_f32 v205, v106, v107
	global_store_dwordx4 v212, v[202:205], s[6:7]
	v_cvt_pk_bf16_f32 v206, v100, v101
	v_cvt_pk_bf16_f32 v207, v102, v103
	v_cvt_pk_bf16_f32 v208, v96, v97
	v_cvt_pk_bf16_f32 v209, v98, v99
	global_store_dwordx4 v212, v[206:209], s[6:7] offset:256
	s_add_u32 s6, s6, 0x10000
	s_addc_u32 s7, s7, 0
	v_cvt_pk_bf16_f32 v202, v92, v93
	v_cvt_pk_bf16_f32 v203, v94, v95
	v_cvt_pk_bf16_f32 v204, v88, v89
	v_cvt_pk_bf16_f32 v205, v90, v91
	global_store_dwordx4 v212, v[202:205], s[6:7]
	v_cvt_pk_bf16_f32 v206, v84, v85
	v_cvt_pk_bf16_f32 v207, v86, v87
	v_cvt_pk_bf16_f32 v208, v80, v81
	v_cvt_pk_bf16_f32 v209, v82, v83
	global_store_dwordx4 v212, v[206:209], s[6:7] offset:256
	s_add_u32 s6, s6, 0x10000
	s_addc_u32 s7, s7, 0
	v_cvt_pk_bf16_f32 v202, v76, v77
	v_cvt_pk_bf16_f32 v203, v78, v79
	v_cvt_pk_bf16_f32 v204, v72, v73
	v_cvt_pk_bf16_f32 v205, v74, v75
	global_store_dwordx4 v212, v[202:205], s[6:7]
	v_cvt_pk_bf16_f32 v206, v68, v69
	v_cvt_pk_bf16_f32 v207, v70, v71
	v_cvt_pk_bf16_f32 v208, v64, v65
	v_cvt_pk_bf16_f32 v209, v66, v67
	global_store_dwordx4 v212, v[206:209], s[6:7] offset:256
	s_add_u32 s6, s6, 0x50000
	s_addc_u32 s7, s7, 0
	v_cvt_pk_bf16_f32 v202, v60, v61
	v_cvt_pk_bf16_f32 v203, v62, v63
	v_cvt_pk_bf16_f32 v204, v56, v57
	v_cvt_pk_bf16_f32 v205, v58, v59
	global_store_dwordx4 v212, v[202:205], s[6:7]
	v_cvt_pk_bf16_f32 v206, v52, v53
	v_cvt_pk_bf16_f32 v207, v54, v55
	v_cvt_pk_bf16_f32 v208, v48, v49
	v_cvt_pk_bf16_f32 v209, v50, v51
	global_store_dwordx4 v212, v[206:209], s[6:7] offset:256
	s_add_u32 s6, s6, 0x10000
	s_addc_u32 s7, s7, 0
	v_cvt_pk_bf16_f32 v202, v44, v45
	v_cvt_pk_bf16_f32 v203, v46, v47
	v_cvt_pk_bf16_f32 v204, v40, v41
	v_cvt_pk_bf16_f32 v205, v42, v43
	global_store_dwordx4 v212, v[202:205], s[6:7]
	v_cvt_pk_bf16_f32 v206, v36, v37
	v_cvt_pk_bf16_f32 v207, v38, v39
	v_cvt_pk_bf16_f32 v208, v32, v33
	v_cvt_pk_bf16_f32 v209, v34, v35
	global_store_dwordx4 v212, v[206:209], s[6:7] offset:256
	s_add_u32 s6, s6, 0x10000
	s_addc_u32 s7, s7, 0
	v_cvt_pk_bf16_f32 v202, v28, v29
	v_cvt_pk_bf16_f32 v203, v30, v31
	v_cvt_pk_bf16_f32 v204, v24, v25
	v_cvt_pk_bf16_f32 v205, v26, v27
	global_store_dwordx4 v212, v[202:205], s[6:7]
	v_cvt_pk_bf16_f32 v206, v20, v21
	v_cvt_pk_bf16_f32 v207, v22, v23
	v_cvt_pk_bf16_f32 v208, v16, v17
	v_cvt_pk_bf16_f32 v209, v18, v19
	global_store_dwordx4 v212, v[206:209], s[6:7] offset:256
	s_add_u32 s6, s6, 0x10000
	s_addc_u32 s7, s7, 0
	v_cvt_pk_bf16_f32 v202, v12, v13
	v_cvt_pk_bf16_f32 v203, v14, v15
	v_cvt_pk_bf16_f32 v204, v4, v5
	v_cvt_pk_bf16_f32 v205, v6, v7
	global_store_dwordx4 v212, v[202:205], s[6:7]
	v_cvt_pk_bf16_f32 v206, v8, v9
	v_cvt_pk_bf16_f32 v207, v10, v11
	v_cvt_pk_bf16_f32 v208, v0, v1
	v_cvt_pk_bf16_f32 v209, v2, v3
	global_store_dwordx4 v212, v[206:209], s[6:7] offset:256
	v_pk_add_f32 v[162:163], v[162:163], 1.0 op_sel_hi:[1,0]
	v_pk_mul_f32 v[146:147], v[146:147], v[162:163]
	v_pk_add_f32 v[164:165], v[164:165], 1.0 op_sel_hi:[1,0]
	v_pk_mul_f32 v[148:149], v[148:149], v[164:165]
	v_pk_add_f32 v[166:167], v[166:167], 1.0 op_sel_hi:[1,0]
	v_pk_mul_f32 v[150:151], v[150:151], v[166:167]
	v_pk_add_f32 v[168:169], v[168:169], 1.0 op_sel_hi:[1,0]
	v_pk_mul_f32 v[152:153], v[152:153], v[168:169]
	v_pk_add_f32 v[170:171], v[170:171], 1.0 op_sel_hi:[1,0]
	v_pk_mul_f32 v[154:155], v[154:155], v[170:171]
	v_pk_add_f32 v[172:173], v[172:173], 1.0 op_sel_hi:[1,0]
	v_pk_mul_f32 v[156:157], v[156:157], v[172:173]
	v_pk_add_f32 v[174:175], v[174:175], 1.0 op_sel_hi:[1,0]
	v_pk_mul_f32 v[158:159], v[158:159], v[174:175]
	v_pk_add_f32 v[176:177], v[176:177], 1.0 op_sel_hi:[1,0]
	v_pk_mul_f32 v[160:161], v[160:161], v[176:177]
	s_branch .Lo4_exchange
.Lo4_n_out:
	ds_read_b32 v194, v217 offset:4096
	ds_read_b32 v195, v217 offset:4160
	ds_read_b32 v196, v217 offset:4224
	ds_read_b32 v197, v217 offset:4288
	ds_read_b32 v198, v217 offset:4608
	ds_read_b32 v199, v217 offset:4672
	ds_read_b32 v200, v217 offset:4736
	ds_read_b32 v201, v217 offset:4800
	s_waitcnt lgkmcnt(0)
	v_pk_mul_f32 v[236:237], v[126:127], v[194:195] op_sel_hi:[1,0]
	v_pk_mul_f32 v[236:237], v[146:147], v[236:237]
	v_pk_add_f32 v[236:237], v[178:179], v[236:237]
	v_cvt_pk_bf16_f32 v202, v236, v237
	v_pk_mul_f32 v[236:237], v[128:129], v[194:195] op_sel_hi:[1,0]
	v_pk_mul_f32 v[236:237], v[148:149], v[236:237]
	v_pk_add_f32 v[236:237], v[180:181], v[236:237]
	v_cvt_pk_bf16_f32 v203, v236, v237
	v_pk_mul_f32 v[236:237], v[122:123], v[194:195] op_sel_hi:[1,0]
	v_pk_fma_f32 v[236:237], v[150:151], v[236:237], v[182:183]
	v_cvt_pk_bf16_f32 v204, v236, v237
	v_pk_mul_f32 v[236:237], v[124:125], v[194:195] op_sel_hi:[1,0]
	v_pk_fma_f32 v[236:237], v[152:153], v[236:237], v[184:185]
	v_cvt_pk_bf16_f32 v205, v236, v237
	global_store_dwordx4 v213, v[202:205], s[8:9] sc1
	v_pk_mul_f32 v[236:237], v[118:119], v[194:195] op_sel_hi:[1,0]
	v_pk_mul_f32 v[236:237], v[154:155], v[236:237]
	v_pk_add_f32 v[236:237], v[186:187], v[236:237]
	v_cvt_pk_bf16_f32 v206, v236, v237
	v_pk_mul_f32 v[236:237], v[120:121], v[194:195] op_sel_hi:[1,0]
	v_pk_mul_f32 v[236:237], v[156:157], v[236:237]
	v_pk_add_f32 v[236:237], v[188:189], v[236:237]
	v_cvt_pk_bf16_f32 v207, v236, v237
	v_pk_mul_f32 v[236:237], v[114:115], v[194:195] op_sel_hi:[1,0]
	v_pk_fma_f32 v[236:237], v[158:159], v[236:237], v[190:191]
	v_cvt_pk_bf16_f32 v208, v236, v237
	v_pk_mul_f32 v[236:237], v[116:117], v[194:195] op_sel_hi:[1,0]
	v_pk_fma_f32 v[236:237], v[160:161], v[236:237], v[192:193]
	v_cvt_pk_bf16_f32 v209, v236, v237
	global_store_dwordx4 v213, v[206:209], s[8:9] offset:256 sc1
	s_add_u32 s8, s8, 0x8000
	s_addc_u32 s9, s9, 0
	v_pk_mul_f32 v[236:237], v[108:109], v[194:195] op_sel:[0,1] op_sel_hi:[1,1]
	v_pk_mul_f32 v[236:237], v[146:147], v[236:237]
	v_pk_add_f32 v[236:237], v[178:179], v[236:237]
	v_cvt_pk_bf16_f32 v202, v236, v237
	v_pk_mul_f32 v[236:237], v[110:111], v[194:195] op_sel:[0,1] op_sel_hi:[1,1]
	v_pk_mul_f32 v[236:237], v[148:149], v[236:237]
	v_pk_add_f32 v[236:237], v[180:181], v[236:237]
	v_cvt_pk_bf16_f32 v203, v236, v237
	v_pk_mul_f32 v[236:237], v[104:105], v[194:195] op_sel:[0,1] op_sel_hi:[1,1]
	v_pk_fma_f32 v[236:237], v[150:151], v[236:237], v[182:183]
	v_cvt_pk_bf16_f32 v204, v236, v237
	v_pk_mul_f32 v[236:237], v[106:107], v[194:195] op_sel:[0,1] op_sel_hi:[1,1]
	v_pk_fma_f32 v[236:237], v[152:153], v[236:237], v[184:185]
	v_cvt_pk_bf16_f32 v205, v236, v237
	global_store_dwordx4 v213, v[202:205], s[8:9] sc1
	v_pk_mul_f32 v[236:237], v[100:101], v[194:195] op_sel:[0,1] op_sel_hi:[1,1]
	v_pk_mul_f32 v[236:237], v[154:155], v[236:237]
	v_pk_add_f32 v[236:237], v[186:187], v[236:237]
	v_cvt_pk_bf16_f32 v206, v236, v237
	v_pk_mul_f32 v[236:237], v[102:103], v[194:195] op_sel:[0,1] op_sel_hi:[1,1]
	v_pk_mul_f32 v[236:237], v[156:157], v[236:237]
	v_pk_add_f32 v[236:237], v[188:189], v[236:237]
	v_cvt_pk_bf16_f32 v207, v236, v237
	v_pk_mul_f32 v[236:237], v[96:97], v[194:195] op_sel:[0,1] op_sel_hi:[1,1]
	v_pk_fma_f32 v[236:237], v[158:159], v[236:237], v[190:191]
	v_cvt_pk_bf16_f32 v208, v236, v237
	v_pk_mul_f32 v[236:237], v[98:99], v[194:195] op_sel:[0,1] op_sel_hi:[1,1]
	v_pk_fma_f32 v[236:237], v[160:161], v[236:237], v[192:193]
	v_cvt_pk_bf16_f32 v209, v236, v237
	global_store_dwordx4 v213, v[206:209], s[8:9] offset:256 sc1
	s_add_u32 s8, s8, 0x8000
	s_addc_u32 s9, s9, 0
	v_pk_mul_f32 v[236:237], v[92:93], v[196:197] op_sel_hi:[1,0]
	v_pk_mul_f32 v[236:237], v[146:147], v[236:237]
	v_pk_add_f32 v[236:237], v[178:179], v[236:237]
	v_cvt_pk_bf16_f32 v202, v236, v237
	v_pk_mul_f32 v[236:237], v[94:95], v[196:197] op_sel_hi:[1,0]
	v_pk_mul_f32 v[236:237], v[148:149], v[236:237]
	v_pk_add_f32 v[236:237], v[180:181], v[236:237]
	v_cvt_pk_bf16_f32 v203, v236, v237
	v_pk_mul_f32 v[236:237], v[88:89], v[196:197] op_sel_hi:[1,0]
	v_pk_fma_f32 v[236:237], v[150:151], v[236:237], v[182:183]
	v_cvt_pk_bf16_f32 v204, v236, v237
	v_pk_mul_f32 v[236:237], v[90:91], v[196:197] op_sel_hi:[1,0]
	v_pk_fma_f32 v[236:237], v[152:153], v[236:237], v[184:185]
	v_cvt_pk_bf16_f32 v205, v236, v237
	global_store_dwordx4 v213, v[202:205], s[8:9] sc1
	v_pk_mul_f32 v[236:237], v[84:85], v[196:197] op_sel_hi:[1,0]
	v_pk_mul_f32 v[236:237], v[154:155], v[236:237]
	v_pk_add_f32 v[236:237], v[186:187], v[236:237]
	v_cvt_pk_bf16_f32 v206, v236, v237
	v_pk_mul_f32 v[236:237], v[86:87], v[196:197] op_sel_hi:[1,0]
	v_pk_mul_f32 v[236:237], v[156:157], v[236:237]
	v_pk_add_f32 v[236:237], v[188:189], v[236:237]
	v_cvt_pk_bf16_f32 v207, v236, v237
	v_pk_mul_f32 v[236:237], v[80:81], v[196:197] op_sel_hi:[1,0]
	v_pk_fma_f32 v[236:237], v[158:159], v[236:237], v[190:191]
	v_cvt_pk_bf16_f32 v208, v236, v237
	v_pk_mul_f32 v[236:237], v[82:83], v[196:197] op_sel_hi:[1,0]
	v_pk_fma_f32 v[236:237], v[160:161], v[236:237], v[192:193]
	v_cvt_pk_bf16_f32 v209, v236, v237
	global_store_dwordx4 v213, v[206:209], s[8:9] offset:256 sc1
	s_add_u32 s8, s8, 0x8000
	s_addc_u32 s9, s9, 0
	v_pk_mul_f32 v[236:237], v[76:77], v[196:197] op_sel:[0,1] op_sel_hi:[1,1]
	v_pk_mul_f32 v[236:237], v[146:147], v[236:237]
	v_pk_add_f32 v[236:237], v[178:179], v[236:237]
	v_cvt_pk_bf16_f32 v202, v236, v237
	v_pk_mul_f32 v[236:237], v[78:79], v[196:197] op_sel:[0,1] op_sel_hi:[1,1]
	v_pk_mul_f32 v[236:237], v[148:149], v[236:237]
	v_pk_add_f32 v[236:237], v[180:181], v[236:237]
	v_cvt_pk_bf16_f32 v203, v236, v237
	v_pk_mul_f32 v[236:237], v[72:73], v[196:197] op_sel:[0,1] op_sel_hi:[1,1]
	v_pk_fma_f32 v[236:237], v[150:151], v[236:237], v[182:183]
	v_cvt_pk_bf16_f32 v204, v236, v237
	v_pk_mul_f32 v[236:237], v[74:75], v[196:197] op_sel:[0,1] op_sel_hi:[1,1]
	v_pk_fma_f32 v[236:237], v[152:153], v[236:237], v[184:185]
	v_cvt_pk_bf16_f32 v205, v236, v237
	global_store_dwordx4 v213, v[202:205], s[8:9] sc1
	v_pk_mul_f32 v[236:237], v[68:69], v[196:197] op_sel:[0,1] op_sel_hi:[1,1]
	v_pk_mul_f32 v[236:237], v[154:155], v[236:237]
	v_pk_add_f32 v[236:237], v[186:187], v[236:237]
	v_cvt_pk_bf16_f32 v206, v236, v237
	v_pk_mul_f32 v[236:237], v[70:71], v[196:197] op_sel:[0,1] op_sel_hi:[1,1]
	v_pk_mul_f32 v[236:237], v[156:157], v[236:237]
	v_pk_add_f32 v[236:237], v[188:189], v[236:237]
	v_cvt_pk_bf16_f32 v207, v236, v237
	v_pk_mul_f32 v[236:237], v[64:65], v[196:197] op_sel:[0,1] op_sel_hi:[1,1]
	v_pk_fma_f32 v[236:237], v[158:159], v[236:237], v[190:191]
	v_cvt_pk_bf16_f32 v208, v236, v237
	v_pk_mul_f32 v[236:237], v[66:67], v[196:197] op_sel:[0,1] op_sel_hi:[1,1]
	v_pk_fma_f32 v[236:237], v[160:161], v[236:237], v[192:193]
	v_cvt_pk_bf16_f32 v209, v236, v237
	global_store_dwordx4 v213, v[206:209], s[8:9] offset:256 sc1
	s_add_u32 s8, s8, 0x28000
	s_addc_u32 s9, s9, 0
	v_pk_mul_f32 v[236:237], v[60:61], v[198:199] op_sel_hi:[1,0]
	v_pk_mul_f32 v[236:237], v[146:147], v[236:237]
	v_pk_add_f32 v[236:237], v[178:179], v[236:237]
	v_cvt_pk_bf16_f32 v202, v236, v237
	v_pk_mul_f32 v[236:237], v[62:63], v[198:199] op_sel_hi:[1,0]
	v_pk_mul_f32 v[236:237], v[148:149], v[236:237]
	v_pk_add_f32 v[236:237], v[180:181], v[236:237]
	v_cvt_pk_bf16_f32 v203, v236, v237
	v_pk_mul_f32 v[236:237], v[56:57], v[198:199] op_sel_hi:[1,0]
	v_pk_fma_f32 v[236:237], v[150:151], v[236:237], v[182:183]
	v_cvt_pk_bf16_f32 v204, v236, v237
	v_pk_mul_f32 v[236:237], v[58:59], v[198:199] op_sel_hi:[1,0]
	v_pk_fma_f32 v[236:237], v[152:153], v[236:237], v[184:185]
	v_cvt_pk_bf16_f32 v205, v236, v237
	global_store_dwordx4 v213, v[202:205], s[8:9] sc1
	v_pk_mul_f32 v[236:237], v[52:53], v[198:199] op_sel_hi:[1,0]
	v_pk_mul_f32 v[236:237], v[154:155], v[236:237]
	v_pk_add_f32 v[236:237], v[186:187], v[236:237]
	v_cvt_pk_bf16_f32 v206, v236, v237
	v_pk_mul_f32 v[236:237], v[54:55], v[198:199] op_sel_hi:[1,0]
	v_pk_mul_f32 v[236:237], v[156:157], v[236:237]
	v_pk_add_f32 v[236:237], v[188:189], v[236:237]
	v_cvt_pk_bf16_f32 v207, v236, v237
	v_pk_mul_f32 v[236:237], v[48:49], v[198:199] op_sel_hi:[1,0]
	v_pk_fma_f32 v[236:237], v[158:159], v[236:237], v[190:191]
	v_cvt_pk_bf16_f32 v208, v236, v237
	v_pk_mul_f32 v[236:237], v[50:51], v[198:199] op_sel_hi:[1,0]
	v_pk_fma_f32 v[236:237], v[160:161], v[236:237], v[192:193]
	v_cvt_pk_bf16_f32 v209, v236, v237
	global_store_dwordx4 v213, v[206:209], s[8:9] offset:256 sc1
	s_add_u32 s8, s8, 0x8000
	s_addc_u32 s9, s9, 0
	v_pk_mul_f32 v[236:237], v[44:45], v[198:199] op_sel:[0,1] op_sel_hi:[1,1]
	v_pk_mul_f32 v[236:237], v[146:147], v[236:237]
	v_pk_add_f32 v[236:237], v[178:179], v[236:237]
	v_cvt_pk_bf16_f32 v202, v236, v237
	v_pk_mul_f32 v[236:237], v[46:47], v[198:199] op_sel:[0,1] op_sel_hi:[1,1]
	v_pk_mul_f32 v[236:237], v[148:149], v[236:237]
	v_pk_add_f32 v[236:237], v[180:181], v[236:237]
	v_cvt_pk_bf16_f32 v203, v236, v237
	v_pk_mul_f32 v[236:237], v[40:41], v[198:199] op_sel:[0,1] op_sel_hi:[1,1]
	v_pk_fma_f32 v[236:237], v[150:151], v[236:237], v[182:183]
	v_cvt_pk_bf16_f32 v204, v236, v237
	v_pk_mul_f32 v[236:237], v[42:43], v[198:199] op_sel:[0,1] op_sel_hi:[1,1]
	v_pk_fma_f32 v[236:237], v[152:153], v[236:237], v[184:185]
	v_cvt_pk_bf16_f32 v205, v236, v237
	global_store_dwordx4 v213, v[202:205], s[8:9] sc1
	v_pk_mul_f32 v[236:237], v[36:37], v[198:199] op_sel:[0,1] op_sel_hi:[1,1]
	v_pk_mul_f32 v[236:237], v[154:155], v[236:237]
	v_pk_add_f32 v[236:237], v[186:187], v[236:237]
	v_cvt_pk_bf16_f32 v206, v236, v237
	v_pk_mul_f32 v[236:237], v[38:39], v[198:199] op_sel:[0,1] op_sel_hi:[1,1]
	v_pk_mul_f32 v[236:237], v[156:157], v[236:237]
	v_pk_add_f32 v[236:237], v[188:189], v[236:237]
	v_cvt_pk_bf16_f32 v207, v236, v237
	v_pk_mul_f32 v[236:237], v[32:33], v[198:199] op_sel:[0,1] op_sel_hi:[1,1]
	v_pk_fma_f32 v[236:237], v[158:159], v[236:237], v[190:191]
	v_cvt_pk_bf16_f32 v208, v236, v237
	v_pk_mul_f32 v[236:237], v[34:35], v[198:199] op_sel:[0,1] op_sel_hi:[1,1]
	v_pk_fma_f32 v[236:237], v[160:161], v[236:237], v[192:193]
	v_cvt_pk_bf16_f32 v209, v236, v237
	global_store_dwordx4 v213, v[206:209], s[8:9] offset:256 sc1
	s_add_u32 s8, s8, 0x8000
	s_addc_u32 s9, s9, 0
	v_pk_mul_f32 v[236:237], v[28:29], v[200:201] op_sel_hi:[1,0]
	v_pk_mul_f32 v[236:237], v[146:147], v[236:237]
	v_pk_add_f32 v[236:237], v[178:179], v[236:237]
	v_cvt_pk_bf16_f32 v202, v236, v237
	v_pk_mul_f32 v[236:237], v[30:31], v[200:201] op_sel_hi:[1,0]
	v_pk_mul_f32 v[236:237], v[148:149], v[236:237]
	v_pk_add_f32 v[236:237], v[180:181], v[236:237]
	v_cvt_pk_bf16_f32 v203, v236, v237
	v_pk_mul_f32 v[236:237], v[24:25], v[200:201] op_sel_hi:[1,0]
	v_pk_fma_f32 v[236:237], v[150:151], v[236:237], v[182:183]
	v_cvt_pk_bf16_f32 v204, v236, v237
	v_pk_mul_f32 v[236:237], v[26:27], v[200:201] op_sel_hi:[1,0]
	v_pk_fma_f32 v[236:237], v[152:153], v[236:237], v[184:185]
	v_cvt_pk_bf16_f32 v205, v236, v237
	global_store_dwordx4 v213, v[202:205], s[8:9] sc1
	v_pk_mul_f32 v[236:237], v[20:21], v[200:201] op_sel_hi:[1,0]
	v_pk_mul_f32 v[236:237], v[154:155], v[236:237]
	v_pk_add_f32 v[236:237], v[186:187], v[236:237]
	v_cvt_pk_bf16_f32 v206, v236, v237
	v_pk_mul_f32 v[236:237], v[22:23], v[200:201] op_sel_hi:[1,0]
	v_pk_mul_f32 v[236:237], v[156:157], v[236:237]
	v_pk_add_f32 v[236:237], v[188:189], v[236:237]
	v_cvt_pk_bf16_f32 v207, v236, v237
	v_pk_mul_f32 v[236:237], v[16:17], v[200:201] op_sel_hi:[1,0]
	v_pk_fma_f32 v[236:237], v[158:159], v[236:237], v[190:191]
	v_cvt_pk_bf16_f32 v208, v236, v237
	v_pk_mul_f32 v[236:237], v[18:19], v[200:201] op_sel_hi:[1,0]
	v_pk_fma_f32 v[236:237], v[160:161], v[236:237], v[192:193]
	v_cvt_pk_bf16_f32 v209, v236, v237
	global_store_dwordx4 v213, v[206:209], s[8:9] offset:256 sc1
	s_add_u32 s8, s8, 0x8000
	s_addc_u32 s9, s9, 0
	v_pk_mul_f32 v[236:237], v[12:13], v[200:201] op_sel:[0,1] op_sel_hi:[1,1]
	v_pk_mul_f32 v[236:237], v[146:147], v[236:237]
	v_pk_add_f32 v[236:237], v[178:179], v[236:237]
	v_cvt_pk_bf16_f32 v202, v236, v237
	v_pk_mul_f32 v[236:237], v[14:15], v[200:201] op_sel:[0,1] op_sel_hi:[1,1]
	v_pk_mul_f32 v[236:237], v[148:149], v[236:237]
	v_pk_add_f32 v[236:237], v[180:181], v[236:237]
	v_cvt_pk_bf16_f32 v203, v236, v237
	v_pk_mul_f32 v[236:237], v[4:5], v[200:201] op_sel:[0,1] op_sel_hi:[1,1]
	v_pk_fma_f32 v[236:237], v[150:151], v[236:237], v[182:183]
	v_cvt_pk_bf16_f32 v204, v236, v237
	v_pk_mul_f32 v[236:237], v[6:7], v[200:201] op_sel:[0,1] op_sel_hi:[1,1]
	v_pk_fma_f32 v[236:237], v[152:153], v[236:237], v[184:185]
	v_cvt_pk_bf16_f32 v205, v236, v237
	global_store_dwordx4 v213, v[202:205], s[8:9] sc1
	v_pk_mul_f32 v[236:237], v[8:9], v[200:201] op_sel:[0,1] op_sel_hi:[1,1]
	v_pk_mul_f32 v[236:237], v[154:155], v[236:237]
	v_pk_add_f32 v[236:237], v[186:187], v[236:237]
	v_cvt_pk_bf16_f32 v206, v236, v237
	v_pk_mul_f32 v[236:237], v[10:11], v[200:201] op_sel:[0,1] op_sel_hi:[1,1]
	v_pk_mul_f32 v[236:237], v[156:157], v[236:237]
	v_pk_add_f32 v[236:237], v[188:189], v[236:237]
	v_cvt_pk_bf16_f32 v207, v236, v237
	v_pk_mul_f32 v[236:237], v[0:1], v[200:201] op_sel:[0,1] op_sel_hi:[1,1]
	v_pk_fma_f32 v[236:237], v[158:159], v[236:237], v[190:191]
	v_cvt_pk_bf16_f32 v208, v236, v237
	v_pk_mul_f32 v[236:237], v[2:3], v[200:201] op_sel:[0,1] op_sel_hi:[1,1]
	v_pk_fma_f32 v[236:237], v[160:161], v[236:237], v[192:193]
	v_cvt_pk_bf16_f32 v209, v236, v237
	global_store_dwordx4 v213, v[206:209], s[8:9] offset:256 sc1
	s_waitcnt vmcnt(0)
	s_mov_b64 exec, 1
	global_atomic_add v113, v246, s[26:27]
	s_mov_b64 exec, -1
	s_branch .LBB0_1145
.Lo4_tail_last:
	global_load_dwordx4 v[146:149], v210, s[20:21] offset:0
	global_load_dwordx4 v[150:153], v210, s[20:21] offset:16
	global_load_dwordx4 v[154:157], v210, s[20:21] offset:512
	global_load_dwordx4 v[158:161], v210, s[20:21] offset:528
	s_waitcnt lgkmcnt(0)
	s_barrier
	s_lshl_b32 s28, s74, 2
	s_add_u32 s28, s22, s28
	s_addc_u32 s29, s23, 0
	s_mov_b32 exec_lo, -1
	s_mov_b32 exec_hi, 0
	ds_read_b128 v[236:239], v215
	s_waitcnt lgkmcnt(0)
	v_add_f32_e32 v236, v236, v237
	v_add_f32_e32 v238, v238, v239
	v_add_f32_e32 v236, v236, v238
	global_store_dword v215, v236, s[28:29] sc1
	s_mov_b64 exec, -1
	s_waitcnt vmcnt(0)
	s_mov_b64 exec, 1
	global_atomic_add v113, v246, s[24:25]
	s_mov_b64 exec, -1
	s_branch .Lo4_exchange
.Lo4_l_out:
	ds_read_b32 v194, v217 offset:4096
	ds_read_b32 v195, v217 offset:4160
	ds_read_b32 v196, v217 offset:4224
	ds_read_b32 v197, v217 offset:4288
	ds_read_b32 v198, v217 offset:4608
	ds_read_b32 v199, v217 offset:4672
	ds_read_b32 v200, v217 offset:4736
	ds_read_b32 v201, v217 offset:4800
	s_waitcnt lgkmcnt(0)
	v_pk_mul_f32 v[236:237], v[126:127], v[194:195] op_sel_hi:[1,0]
	v_pk_mul_f32 v[202:203], v[146:147], v[236:237]
	v_pk_mul_f32 v[236:237], v[128:129], v[194:195] op_sel_hi:[1,0]
	v_pk_mul_f32 v[204:205], v[148:149], v[236:237]
	global_store_dwordx4 v211, v[202:205], s[8:9] offset:0
	v_pk_mul_f32 v[236:237], v[122:123], v[194:195] op_sel_hi:[1,0]
	v_pk_mul_f32 v[206:207], v[150:151], v[236:237]
	v_pk_mul_f32 v[236:237], v[124:125], v[194:195] op_sel_hi:[1,0]
	v_pk_mul_f32 v[208:209], v[152:153], v[236:237]
	global_store_dwordx4 v211, v[206:209], s[8:9] offset:16
	v_pk_mul_f32 v[236:237], v[118:119], v[194:195] op_sel_hi:[1,0]
	v_pk_mul_f32 v[202:203], v[154:155], v[236:237]
	v_pk_mul_f32 v[236:237], v[120:121], v[194:195] op_sel_hi:[1,0]
	v_pk_mul_f32 v[204:205], v[156:157], v[236:237]
	global_store_dwordx4 v211, v[202:205], s[8:9] offset:512
	v_pk_mul_f32 v[236:237], v[114:115], v[194:195] op_sel_hi:[1,0]
	v_pk_mul_f32 v[206:207], v[158:159], v[236:237]
	v_pk_mul_f32 v[236:237], v[116:117], v[194:195] op_sel_hi:[1,0]
	v_pk_mul_f32 v[208:209], v[160:161], v[236:237]
	global_store_dwordx4 v211, v[206:209], s[8:9] offset:528
	s_add_u32 s8, s8, 0x10000
	s_addc_u32 s9, s9, 0
	v_pk_mul_f32 v[236:237], v[108:109], v[194:195] op_sel:[0,1] op_sel_hi:[1,1]
	v_pk_mul_f32 v[202:203], v[146:147], v[236:237]
	v_pk_mul_f32 v[236:237], v[110:111], v[194:195] op_sel:[0,1] op_sel_hi:[1,1]
	v_pk_mul_f32 v[204:205], v[148:149], v[236:237]
	global_store_dwordx4 v211, v[202:205], s[8:9] offset:0
	v_pk_mul_f32 v[236:237], v[104:105], v[194:195] op_sel:[0,1] op_sel_hi:[1,1]
	v_pk_mul_f32 v[206:207], v[150:151], v[236:237]
	v_pk_mul_f32 v[236:237], v[106:107], v[194:195] op_sel:[0,1] op_sel_hi:[1,1]
	v_pk_mul_f32 v[208:209], v[152:153], v[236:237]
	global_store_dwordx4 v211, v[206:209], s[8:9] offset:16
	v_pk_mul_f32 v[236:237], v[100:101], v[194:195] op_sel:[0,1] op_sel_hi:[1,1]
	v_pk_mul_f32 v[202:203], v[154:155], v[236:237]
	v_pk_mul_f32 v[236:237], v[102:103], v[194:195] op_sel:[0,1] op_sel_hi:[1,1]
	v_pk_mul_f32 v[204:205], v[156:157], v[236:237]
	global_store_dwordx4 v211, v[202:205], s[8:9] offset:512
	v_pk_mul_f32 v[236:237], v[96:97], v[194:195] op_sel:[0,1] op_sel_hi:[1,1]
	v_pk_mul_f32 v[206:207], v[158:159], v[236:237]
	v_pk_mul_f32 v[236:237], v[98:99], v[194:195] op_sel:[0,1] op_sel_hi:[1,1]
	v_pk_mul_f32 v[208:209], v[160:161], v[236:237]
	global_store_dwordx4 v211, v[206:209], s[8:9] offset:528
	s_add_u32 s8, s8, 0x10000
	s_addc_u32 s9, s9, 0
	v_pk_mul_f32 v[236:237], v[92:93], v[196:197] op_sel_hi:[1,0]
	v_pk_mul_f32 v[202:203], v[146:147], v[236:237]
	v_pk_mul_f32 v[236:237], v[94:95], v[196:197] op_sel_hi:[1,0]
	v_pk_mul_f32 v[204:205], v[148:149], v[236:237]
	global_store_dwordx4 v211, v[202:205], s[8:9] offset:0
	v_pk_mul_f32 v[236:237], v[88:89], v[196:197] op_sel_hi:[1,0]
	v_pk_mul_f32 v[206:207], v[150:151], v[236:237]
	v_pk_mul_f32 v[236:237], v[90:91], v[196:197] op_sel_hi:[1,0]
	v_pk_mul_f32 v[208:209], v[152:153], v[236:237]
	global_store_dwordx4 v211, v[206:209], s[8:9] offset:16
	v_pk_mul_f32 v[236:237], v[84:85], v[196:197] op_sel_hi:[1,0]
	v_pk_mul_f32 v[202:203], v[154:155], v[236:237]
	v_pk_mul_f32 v[236:237], v[86:87], v[196:197] op_sel_hi:[1,0]
	v_pk_mul_f32 v[204:205], v[156:157], v[236:237]
	global_store_dwordx4 v211, v[202:205], s[8:9] offset:512
	v_pk_mul_f32 v[236:237], v[80:81], v[196:197] op_sel_hi:[1,0]
	v_pk_mul_f32 v[206:207], v[158:159], v[236:237]
	v_pk_mul_f32 v[236:237], v[82:83], v[196:197] op_sel_hi:[1,0]
	v_pk_mul_f32 v[208:209], v[160:161], v[236:237]
	global_store_dwordx4 v211, v[206:209], s[8:9] offset:528
	s_add_u32 s8, s8, 0x10000
	s_addc_u32 s9, s9, 0
	v_pk_mul_f32 v[236:237], v[76:77], v[196:197] op_sel:[0,1] op_sel_hi:[1,1]
	v_pk_mul_f32 v[202:203], v[146:147], v[236:237]
	v_pk_mul_f32 v[236:237], v[78:79], v[196:197] op_sel:[0,1] op_sel_hi:[1,1]
	v_pk_mul_f32 v[204:205], v[148:149], v[236:237]
	global_store_dwordx4 v211, v[202:205], s[8:9] offset:0
	v_pk_mul_f32 v[236:237], v[72:73], v[196:197] op_sel:[0,1] op_sel_hi:[1,1]
	v_pk_mul_f32 v[206:207], v[150:151], v[236:237]
	v_pk_mul_f32 v[236:237], v[74:75], v[196:197] op_sel:[0,1] op_sel_hi:[1,1]
	v_pk_mul_f32 v[208:209], v[152:153], v[236:237]
	global_store_dwordx4 v211, v[206:209], s[8:9] offset:16
	v_pk_mul_f32 v[236:237], v[68:69], v[196:197] op_sel:[0,1] op_sel_hi:[1,1]
	v_pk_mul_f32 v[202:203], v[154:155], v[236:237]
	v_pk_mul_f32 v[236:237], v[70:71], v[196:197] op_sel:[0,1] op_sel_hi:[1,1]
	v_pk_mul_f32 v[204:205], v[156:157], v[236:237]
	global_store_dwordx4 v211, v[202:205], s[8:9] offset:512
	v_pk_mul_f32 v[236:237], v[64:65], v[196:197] op_sel:[0,1] op_sel_hi:[1,1]
	v_pk_mul_f32 v[206:207], v[158:159], v[236:237]
	v_pk_mul_f32 v[236:237], v[66:67], v[196:197] op_sel:[0,1] op_sel_hi:[1,1]
	v_pk_mul_f32 v[208:209], v[160:161], v[236:237]
	global_store_dwordx4 v211, v[206:209], s[8:9] offset:528
	s_add_u32 s8, s8, 0x50000
	s_addc_u32 s9, s9, 0
	v_pk_mul_f32 v[236:237], v[60:61], v[198:199] op_sel_hi:[1,0]
	v_pk_mul_f32 v[202:203], v[146:147], v[236:237]
	v_pk_mul_f32 v[236:237], v[62:63], v[198:199] op_sel_hi:[1,0]
	v_pk_mul_f32 v[204:205], v[148:149], v[236:237]
	global_store_dwordx4 v211, v[202:205], s[8:9] offset:0
	v_pk_mul_f32 v[236:237], v[56:57], v[198:199] op_sel_hi:[1,0]
	v_pk_mul_f32 v[206:207], v[150:151], v[236:237]
	v_pk_mul_f32 v[236:237], v[58:59], v[198:199] op_sel_hi:[1,0]
	v_pk_mul_f32 v[208:209], v[152:153], v[236:237]
	global_store_dwordx4 v211, v[206:209], s[8:9] offset:16
	v_pk_mul_f32 v[236:237], v[52:53], v[198:199] op_sel_hi:[1,0]
	v_pk_mul_f32 v[202:203], v[154:155], v[236:237]
	v_pk_mul_f32 v[236:237], v[54:55], v[198:199] op_sel_hi:[1,0]
	v_pk_mul_f32 v[204:205], v[156:157], v[236:237]
	global_store_dwordx4 v211, v[202:205], s[8:9] offset:512
	v_pk_mul_f32 v[236:237], v[48:49], v[198:199] op_sel_hi:[1,0]
	v_pk_mul_f32 v[206:207], v[158:159], v[236:237]
	v_pk_mul_f32 v[236:237], v[50:51], v[198:199] op_sel_hi:[1,0]
	v_pk_mul_f32 v[208:209], v[160:161], v[236:237]
	global_store_dwordx4 v211, v[206:209], s[8:9] offset:528
	s_add_u32 s8, s8, 0x10000
	s_addc_u32 s9, s9, 0
	v_pk_mul_f32 v[236:237], v[44:45], v[198:199] op_sel:[0,1] op_sel_hi:[1,1]
	v_pk_mul_f32 v[202:203], v[146:147], v[236:237]
	v_pk_mul_f32 v[236:237], v[46:47], v[198:199] op_sel:[0,1] op_sel_hi:[1,1]
	v_pk_mul_f32 v[204:205], v[148:149], v[236:237]
	global_store_dwordx4 v211, v[202:205], s[8:9] offset:0
	v_pk_mul_f32 v[236:237], v[40:41], v[198:199] op_sel:[0,1] op_sel_hi:[1,1]
	v_pk_mul_f32 v[206:207], v[150:151], v[236:237]
	v_pk_mul_f32 v[236:237], v[42:43], v[198:199] op_sel:[0,1] op_sel_hi:[1,1]
	v_pk_mul_f32 v[208:209], v[152:153], v[236:237]
	global_store_dwordx4 v211, v[206:209], s[8:9] offset:16
	v_pk_mul_f32 v[236:237], v[36:37], v[198:199] op_sel:[0,1] op_sel_hi:[1,1]
	v_pk_mul_f32 v[202:203], v[154:155], v[236:237]
	v_pk_mul_f32 v[236:237], v[38:39], v[198:199] op_sel:[0,1] op_sel_hi:[1,1]
	v_pk_mul_f32 v[204:205], v[156:157], v[236:237]
	global_store_dwordx4 v211, v[202:205], s[8:9] offset:512
	v_pk_mul_f32 v[236:237], v[32:33], v[198:199] op_sel:[0,1] op_sel_hi:[1,1]
	v_pk_mul_f32 v[206:207], v[158:159], v[236:237]
	v_pk_mul_f32 v[236:237], v[34:35], v[198:199] op_sel:[0,1] op_sel_hi:[1,1]
	v_pk_mul_f32 v[208:209], v[160:161], v[236:237]
	global_store_dwordx4 v211, v[206:209], s[8:9] offset:528
	s_add_u32 s8, s8, 0x10000
	s_addc_u32 s9, s9, 0
	v_pk_mul_f32 v[236:237], v[28:29], v[200:201] op_sel_hi:[1,0]
	v_pk_mul_f32 v[202:203], v[146:147], v[236:237]
	v_pk_mul_f32 v[236:237], v[30:31], v[200:201] op_sel_hi:[1,0]
	v_pk_mul_f32 v[204:205], v[148:149], v[236:237]
	global_store_dwordx4 v211, v[202:205], s[8:9] offset:0
	v_pk_mul_f32 v[236:237], v[24:25], v[200:201] op_sel_hi:[1,0]
	v_pk_mul_f32 v[206:207], v[150:151], v[236:237]
	v_pk_mul_f32 v[236:237], v[26:27], v[200:201] op_sel_hi:[1,0]
	v_pk_mul_f32 v[208:209], v[152:153], v[236:237]
	global_store_dwordx4 v211, v[206:209], s[8:9] offset:16
	v_pk_mul_f32 v[236:237], v[20:21], v[200:201] op_sel_hi:[1,0]
	v_pk_mul_f32 v[202:203], v[154:155], v[236:237]
	v_pk_mul_f32 v[236:237], v[22:23], v[200:201] op_sel_hi:[1,0]
	v_pk_mul_f32 v[204:205], v[156:157], v[236:237]
	global_store_dwordx4 v211, v[202:205], s[8:9] offset:512
	v_pk_mul_f32 v[236:237], v[16:17], v[200:201] op_sel_hi:[1,0]
	v_pk_mul_f32 v[206:207], v[158:159], v[236:237]
	v_pk_mul_f32 v[236:237], v[18:19], v[200:201] op_sel_hi:[1,0]
	v_pk_mul_f32 v[208:209], v[160:161], v[236:237]
	global_store_dwordx4 v211, v[206:209], s[8:9] offset:528
	s_add_u32 s8, s8, 0x10000
	s_addc_u32 s9, s9, 0
	v_pk_mul_f32 v[236:237], v[12:13], v[200:201] op_sel:[0,1] op_sel_hi:[1,1]
	v_pk_mul_f32 v[202:203], v[146:147], v[236:237]
	v_pk_mul_f32 v[236:237], v[14:15], v[200:201] op_sel:[0,1] op_sel_hi:[1,1]
	v_pk_mul_f32 v[204:205], v[148:149], v[236:237]
	global_store_dwordx4 v211, v[202:205], s[8:9] offset:0
	v_pk_mul_f32 v[236:237], v[4:5], v[200:201] op_sel:[0,1] op_sel_hi:[1,1]
	v_pk_mul_f32 v[206:207], v[150:151], v[236:237]
	v_pk_mul_f32 v[236:237], v[6:7], v[200:201] op_sel:[0,1] op_sel_hi:[1,1]
	v_pk_mul_f32 v[208:209], v[152:153], v[236:237]
	global_store_dwordx4 v211, v[206:209], s[8:9] offset:16
	v_pk_mul_f32 v[236:237], v[8:9], v[200:201] op_sel:[0,1] op_sel_hi:[1,1]
	v_pk_mul_f32 v[202:203], v[154:155], v[236:237]
	v_pk_mul_f32 v[236:237], v[10:11], v[200:201] op_sel:[0,1] op_sel_hi:[1,1]
	v_pk_mul_f32 v[204:205], v[156:157], v[236:237]
	global_store_dwordx4 v211, v[202:205], s[8:9] offset:512
	v_pk_mul_f32 v[236:237], v[0:1], v[200:201] op_sel:[0,1] op_sel_hi:[1,1]
	v_pk_mul_f32 v[206:207], v[158:159], v[236:237]
	v_pk_mul_f32 v[236:237], v[2:3], v[200:201] op_sel:[0,1] op_sel_hi:[1,1]
	v_pk_mul_f32 v[208:209], v[160:161], v[236:237]
	global_store_dwordx4 v211, v[206:209], s[8:9] offset:528
	s_branch .LBB0_1145
.Lo4_exchange:
	s_cmp_lg_u32 s33, 0
	s_cbranch_scc1 .Lo4_polled
	s_memrealtime s[16:17]
.Lo4_poll:
	global_load_dword v236, v113, s[24:25] sc1
	s_waitcnt vmcnt(0)
	v_readfirstlane_b32 s28, v236
	s_cmp_gt_u32 s28, 31
	s_cbranch_scc1 .Lo4_polled
	s_memrealtime s[28:29]
	s_waitcnt lgkmcnt(0)
	s_sub_u32 s28, s28, s16
	s_subb_u32 s29, s29, s17
	s_cmp_lg_u32 s29, 0
	s_cbranch_scc1 .Lo4_tmo
	s_cmp_gt_u32 s28, 0x1e8480
	s_cbranch_scc1 .Lo4_tmo
	s_sleep 2
	s_branch .Lo4_poll
.Lo4_tmo:
	s_mov_b64 exec, 1
	global_store_dword v113, v246, s[2:3] sc1
	s_mov_b64 exec, -1
.Lo4_polled:
	s_waitcnt lgkmcnt(0)
	s_barrier
	s_mov_b32 exec_lo, -1
	s_mov_b32 exec_hi, 0
	global_load_dword v236, v215, s[22:23] sc1
	global_load_dword v237, v215, s[22:23] offset:4 sc1
	global_load_dword v238, v215, s[22:23] offset:8 sc1
	global_load_dword v239, v215, s[22:23] offset:12 sc1
	s_waitcnt vmcnt(0)
	v_add_f32_e32 v236, v236, v237
	v_add_f32_e32 v236, v236, v238
	v_add_f32_e32 v236, v236, v239
	v_fmamk_f32 v236, v236, 0x3a800000, v242
	v_rsq_f32_e32 v236, v236
	s_nop 1
	ds_write_b32 v216, v236 offset:4096
	s_mov_b64 exec, -1
	s_waitcnt lgkmcnt(0)
	s_barrier
	s_cmp_eq_u32 s60, 3
	s_cbranch_scc1 .Lo4_l_out
	s_branch .Lo4_n_out
